# static s_setprio 1 for waves 4-7 at kernel entry, all per-segment s_setprio flips removed (strategy 7.4)
# baseline (speedup 1.0000x reference)
; #define LAS __attribute__((address_space(3)))
; #define GPTR(T, p) gptr_<T>(p)
; __global__ void __launch_bounds__(NWAVES * 64, 2) hymba_fwd(Args args) {
;     extern __shared__ __attribute__((aligned(16))) unsigned char lds_raw[];
;     LAS unsigned char* lds = (LAS unsigned char*)lds_raw;
;     volatile LAS unsigned* MISC = (volatile LAS unsigned*)(lds + MISC_OFF);
;     const int tid = threadIdx.x, lane = tid & 63, wave = __builtin_amdgcn_readfirstlane(tid >> 6);
;     const int G0 = gridDim.x, bx0 = blockIdx.x;
;     const int G = G0, bx = bx0;
;     const bool FUSED_FINAL = (N_LAUNCHES == 1) && G == (MP / 256) * (DM / 256);
;     unsigned char* ws = GPTR(unsigned char, args.ws);
;     gu32* ctl = (gu32*)(ws + WS_CTL);
;     for (int u = tid; u < (LDS_BYTES - LDSCTL_OFF) / 4; u += NWAVES * 64) ((LAS unsigned*)(lds + LDSCTL_OFF))[u] = 0u;
;     __syncthreads();
;     XcdBarrier bar; bar.bar = (unsigned*)(ctl + CW_BAR); bar.x = 0; bar.st = nullptr;
;     if (N_LAUNCHES == 1) bar = xcd_barrier_post((unsigned*)(ctl + CW_BAR), MISC + 8);
_Z9hymba_fwd4Args:
	v_readfirstlane_b32 s99, v0
	s_nop 3
	s_and_b32 s99, s99, 0x3ff
	s_lshr_b32 s99, s99, 6
	s_cmp_ge_u32 s99, 4
	s_cbranch_scc0 .Lprio_static_done
	s_setprio 1
.Lprio_static_done:
	s_load_dwordx4 s[4:7], s[0:1], 0x100
	v_writelane_b32 v252, s2, 0
	s_add_u32 s2, s0, 0x120
	s_addc_u32 s3, s1, 0
	v_writelane_b32 v252, s2, 1
	v_lshl_add_u32 v1, v0, 2, 0
	v_add_u32_e32 v1, 0x20000, v1
	v_writelane_b32 v252, s3, 2
	s_load_dword s2, s[0:1], 0x120
	v_mov_b32_e32 v2, 0
	v_readfirstlane_b32 s8, v0
	s_waitcnt lgkmcnt(0)
	v_writelane_b32 v252, s2, 3
	v_writelane_b32 v252, s4, 4
	s_mov_b64 s[2:3], s[6:7]
	ds_write2st64_b32 v1, v2, v2 offset1:8
	ds_write2st64_b32 v1, v2, v2 offset0:16 offset1:24
	v_writelane_b32 v252, s5, 5
	v_writelane_b32 v252, s6, 6
	v_writelane_b32 v252, s7, 7
	v_or_b32_e32 v1, 0x800, v0
	s_mov_b64 s[4:5], -1
	s_and_saveexec_b64 s[6:7], s[4:5]
	v_lshl_add_u32 v3, v1, 2, 0
	v_add_u32_e32 v3, 0x20000, v3
	ds_write_b32 v3, v2
	s_or_b64 exec, exec, s[6:7]
	s_and_saveexec_b64 s[6:7], s[4:5]
	s_add_i32 s4, 0, 0x20000
	v_lshl_add_u32 v1, v1, 2, s4
	v_mov_b32_e32 v2, 0
	ds_write_b32 v1, v2 offset:2048
	s_or_b64 exec, exec, s[6:7]
	v_or_b32_e32 v1, 0xc00, v0
	v_cmp_gt_u32_e64 s[4:5], 7, 6
	v_cmp_gt_u32_e64 s[10:11], 7, 5
	s_and_saveexec_b64 s[6:7], s[10:11]
	v_lshl_add_u32 v2, v1, 2, 0
	v_add_u32_e32 v2, 0x20000, v2
	v_mov_b32_e32 v3, 0
	ds_write_b32 v2, v3
	s_or_b64 exec, exec, s[6:7]
	s_load_dwordx2 s[6:7], s[0:1], 0x110
	s_waitcnt lgkmcnt(0)
	v_writelane_b32 v252, s6, 8
	s_nop 1
	v_writelane_b32 v252, s7, 9
	s_and_saveexec_b64 s[6:7], s[4:5]
	s_add_i32 s4, 0, 0x20000
	v_lshl_add_u32 v1, v1, 2, s4
	v_mov_b32_e32 v2, 0
	ds_write_b32 v1, v2 offset:2048
	s_or_b64 exec, exec, s[6:7]
	s_load_dwordx16 s[12:27], s[0:1], 0x0
	s_add_u32 s2, s2, 0x4000
	s_addc_u32 s3, s3, 0
	s_waitcnt lgkmcnt(0)
	s_barrier
	v_writelane_b32 v252, s12, 10
	v_cmp_eq_u32_e64 s[4:5], 0, v0
	s_nop 0
	v_writelane_b32 v252, s13, 11
	v_writelane_b32 v252, s14, 12
	v_writelane_b32 v252, s15, 13
	v_writelane_b32 v252, s16, 14
	v_writelane_b32 v252, s17, 15
	v_writelane_b32 v252, s18, 16
	v_writelane_b32 v252, s19, 17
	v_writelane_b32 v252, s20, 18
	v_writelane_b32 v252, s21, 19
	v_writelane_b32 v252, s22, 20
	v_writelane_b32 v252, s23, 21
	v_writelane_b32 v252, s24, 22
	v_writelane_b32 v252, s25, 23
	v_writelane_b32 v252, s26, 24
	v_writelane_b32 v252, s27, 25
	s_load_dwordx16 s[12:27], s[0:1], 0x80
	s_waitcnt lgkmcnt(0)
	v_writelane_b32 v252, s12, 26
	s_nop 1
	v_writelane_b32 v252, s13, 27
	v_writelane_b32 v252, s14, 28
	v_writelane_b32 v252, s15, 29
	v_writelane_b32 v252, s16, 30
	v_writelane_b32 v252, s17, 31
	v_writelane_b32 v252, s18, 32
	v_writelane_b32 v252, s19, 33
	v_writelane_b32 v252, s20, 34
	v_writelane_b32 v252, s21, 35
	v_writelane_b32 v252, s22, 36
	v_writelane_b32 v252, s23, 37
	v_writelane_b32 v252, s24, 38
	v_writelane_b32 v252, s25, 39
	v_writelane_b32 v252, s26, 40
	v_writelane_b32 v252, s27, 41
	v_writelane_b32 v252, s2, 42
	s_nop 1
	v_writelane_b32 v252, s3, 43
	s_getreg_b32 s2, hwreg(HW_REG_XCC_ID, 0, 4)
	s_and_b32 s2, s2, 15
	v_writelane_b32 v252, s2, 44
	s_mov_b64 s[2:3], exec
	v_writelane_b32 v252, s4, 45
	s_nop 1
	v_writelane_b32 v252, s5, 46
	s_and_b64 s[4:5], s[2:3], s[4:5]
	s_mov_b64 exec, s[4:5]
	s_cbranch_execz .LBB0_11
	s_mov_b64 s[4:5], exec
	v_mbcnt_lo_u32_b32 v1, s4, 0
	v_mbcnt_hi_u32_b32 v1, s5, v1
	v_cmp_eq_u32_e32 vcc, 0, v1
	s_and_b64 s[6:7], exec, vcc
	s_mov_b64 exec, s[6:7]
	s_cbranch_execz .LBB0_11
	v_readlane_b32 s6, v252, 44
	s_bcnt1_i32_b64 s4, s[4:5]
	s_lshl_b32 s6, s6, 8
	v_mov_b32_e32 v2, s4
	v_readlane_b32 s4, v252, 42
	v_mov_b32_e32 v1, s6
	v_readlane_b32 s5, v252, 43
	s_nop 4
	global_atomic_add v1, v2, s[4:5] offset:1024

; #define PG8_LDX(b) do { if constexpr (XR) { _Pragma("unroll") for (int k = 0; k < 2; ++k) Ax_[k] = *(const PG8_LAS bf16x8*)(lds + XR_OFF + (b) * 2048 + aoffx + k * 1024); } } while (0)
; #define PG8_MMAX() do { if constexpr (XR) { if (hasx) { __builtin_amdgcn_s_setprio(1); if (wr == 0) PG8_MMAX_(B0); else PG8_MMAX_(B1); __builtin_amdgcn_s_setprio(0); } } } while (0)
; #define PG8_WAIT_LOOP() do { if constexpr (XR) PG8_WAIT_V(9); else PG8_WAIT_V(8); } while (0)
; #define PG8_STAGE(bufoff, gbase, voff) do { _Pragma("unroll") for (int _i = 0; _i < 2; ++_i) \
;         __builtin_amdgcn_global_load_lds((const unsigned*)((const char*)(gbase) + (voff)[_i]), (PG8_LAS unsigned*)(lds + (bufoff) + ldsw + _i * 8192), 16, 0, 0); } while (0)
; #define PG8_LDA(dst, b, h) do { _Pragma("unroll") for (int m = 0; m < 4; ++m) _Pragma("unroll") for (int k = 0; k < 2; ++k) dst[m][k] = *(const PG8_LAS bf16x8*)(lds + PG8_SA(b, h) + aoff + m * 2048 + k * 1024); } while (0)
; #define PG8_LDB(dst, b, h) do { _Pragma("unroll") for (int n = 0; n < 2; ++n) _Pragma("unroll") for (int k = 0; k < 2; ++k) dst[n][k] = *(const PG8_LAS bf16x8*)(lds + PG8_SB(b, h) + boff + n * 2048 + k * 1024); } while (0)
; #define PG8_MMA(ai, bj, At, Bt) do { __builtin_amdgcn_s_setprio(1); _Pragma("unroll") for (int m = 0; m < 4; ++m) _Pragma("unroll") for (int n = 0; n < 2; ++n) _Pragma("unroll") for (int k = 0; k < 2; ++k) \
;         acc[ai][bj][m][n] = __builtin_amdgcn_mfma_f32_16x16x32_bf16(Bt[n][k], At[m][k], acc[ai][bj][m][n], 0, 0, 0); __builtin_amdgcn_s_setprio(0); } while (0)
; #define PG8_WAIT_L(n) asm volatile("s_waitcnt lgkmcnt(" #n ")" ::: "memory")
; #define PG8_BAR __builtin_amdgcn_s_barrier()
; #define PG8_SCHED __builtin_amdgcn_sched_barrier(0)
; template <class Epi, class Sched, bool ALIGN_EPI = false, bool SP2 = false, bool DRAIN = true, bool XR = false>
; __device__ __forceinline__ void gemm_phase(PG8_LAS unsigned char* lds, const Gemm g, const Sched& S, const Epi& E) {
;     ...
;             PG8_LDB(B0, 0, 0); PG8_LDB(B1, 0, 1); PG8_SCHED; PG8_LDA(At, 0, 0); PG8_LDX(0); PG8_STAGE(PG8_SA(1, 1), a1 + hstepA, voffA);
;             PG8_WAIT_LOOP(); PG8_WAIT_L(0); PG8_BAR; PG8_MMA(0, 0, At, B0); PG8_MMA(0, 1, At, B1); PG8_MMAX(); PG8_BAR; PG8_SCHED;
.LBB0_1220:
	v_add_u32_e32 v4, 0x10000, v250
	ds_read_b128 v[158:161], v4
	ds_read_b128 v[162:165], v4 offset:1024
	ds_read_b128 v[166:169], v4 offset:2048
	ds_read_b128 v[170:173], v4 offset:3072
	v_add_u32_e32 v4, 0x14000, v250
	s_and_b32 s8, s50, s82
	ds_read_b128 v[142:145], v4
	ds_read_b128 v[146:149], v4 offset:1024
	ds_read_b128 v[150:153], v4 offset:2048
	ds_read_b128 v[154:157], v4 offset:3072
	s_lshr_b32 s84, s8, 2
	s_lshl_b32 s8, s8, 7
	s_lshl_b64 s[6:7], s[84:85], 9
	s_and_b32 s8, s8, 0x100
	s_add_u32 s6, s18, s6
	s_addc_u32 s7, s19, s7
	s_add_u32 s6, s6, s8
	s_addc_u32 s7, s7, 0
	s_add_u32 s6, s6, s10
	v_add_u32_e32 v4, 0x22400, v240
	s_addc_u32 s7, s7, s11
	ds_read_b128 v[182:185], v251
	ds_read_b128 v[186:189], v251 offset:1024
	ds_read_b128 v[190:193], v251 offset:2048
	ds_read_b128 v[194:197], v251 offset:3072
	ds_read_b128 v[198:201], v251 offset:4096
	ds_read_b128 v[202:205], v251 offset:5120
	ds_read_b128 v[224:227], v251 offset:6144
	ds_read_b128 v[228:231], v251 offset:7168
	ds_read_b128 v[174:177], v4
	ds_read_b128 v[178:181], v4 offset:1024
	v_lshl_add_u64 v[4:5], s[6:7], 0, v[214:215]
	v_lshl_add_u64 v[4:5], v[4:5], 0, s[86:87]
	s_add_i32 m0, s64, 0xc000
	s_nop 0
	global_load_lds_dwordx4 v[4:5], off
	v_lshl_add_u64 v[4:5], s[6:7], 0, v[218:219]
	v_lshl_add_u64 v[4:5], v[4:5], 0, s[86:87]
	s_add_i32 m0, s64, 0xe000
	s_nop 0
	global_load_lds_dwordx4 v[4:5], off
	s_waitcnt vmcnt(9)
	s_waitcnt lgkmcnt(0)
	s_barrier
	v_mfma_f32_16x16x32_bf16 v[138:141], v[158:161], v[182:185], v[138:141]
	v_mfma_f32_16x16x32_bf16 v[134:137], v[166:169], v[182:185], v[134:137]
	v_mfma_f32_16x16x32_bf16 v[130:133], v[158:161], v[190:193], v[130:133]
	v_mfma_f32_16x16x32_bf16 v[126:129], v[166:169], v[190:193], v[126:129]
	v_mfma_f32_16x16x32_bf16 v[122:125], v[158:161], v[198:201], v[122:125]
	v_mfma_f32_16x16x32_bf16 v[118:121], v[166:169], v[198:201], v[118:121]
	v_mfma_f32_16x16x32_bf16 v[114:117], v[158:161], v[224:227], v[114:117]
	v_mfma_f32_16x16x32_bf16 v[110:113], v[166:169], v[224:227], v[110:113]
	v_mfma_f32_16x16x32_bf16 v[138:141], v[162:165], v[186:189], v[138:141]
	v_mfma_f32_16x16x32_bf16 v[134:137], v[170:173], v[186:189], v[134:137]
	v_mfma_f32_16x16x32_bf16 v[130:133], v[162:165], v[194:197], v[130:133]
	v_mfma_f32_16x16x32_bf16 v[126:129], v[170:173], v[194:197], v[126:129]
	v_mfma_f32_16x16x32_bf16 v[122:125], v[162:165], v[202:205], v[122:125]
	v_mfma_f32_16x16x32_bf16 v[118:121], v[170:173], v[202:205], v[118:121]
	v_mfma_f32_16x16x32_bf16 v[114:117], v[162:165], v[228:231], v[114:117]
	v_mfma_f32_16x16x32_bf16 v[110:113], v[170:173], v[228:231], v[110:113]
	v_mfma_f32_16x16x32_bf16 v[106:109], v[142:145], v[182:185], v[106:109]
	v_mfma_f32_16x16x32_bf16 v[102:105], v[150:153], v[182:185], v[102:105]
	v_mfma_f32_16x16x32_bf16 v[98:101], v[142:145], v[190:193], v[98:101]
	v_mfma_f32_16x16x32_bf16 v[94:97], v[150:153], v[190:193], v[94:97]
	v_mfma_f32_16x16x32_bf16 v[90:93], v[142:145], v[198:201], v[90:93]
	v_mfma_f32_16x16x32_bf16 v[86:89], v[150:153], v[198:201], v[86:89]
	v_mfma_f32_16x16x32_bf16 v[82:85], v[142:145], v[224:227], v[82:85]
	v_mfma_f32_16x16x32_bf16 v[78:81], v[150:153], v[224:227], v[78:81]
	v_mfma_f32_16x16x32_bf16 v[106:109], v[146:149], v[186:189], v[106:109]
	v_mfma_f32_16x16x32_bf16 v[102:105], v[154:157], v[186:189], v[102:105]
	v_mfma_f32_16x16x32_bf16 v[98:101], v[146:149], v[194:197], v[98:101]
	v_mfma_f32_16x16x32_bf16 v[94:97], v[154:157], v[194:197], v[94:97]
	v_mfma_f32_16x16x32_bf16 v[90:93], v[146:149], v[202:205], v[90:93]
	v_mfma_f32_16x16x32_bf16 v[86:89], v[154:157], v[202:205], v[86:89]
	v_mfma_f32_16x16x32_bf16 v[82:85], v[146:149], v[228:231], v[82:85]
	v_mfma_f32_16x16x32_bf16 v[78:81], v[154:157], v[228:231], v[78:81]
	v_cndmask_b32_e64 v4, 0, 1, s[22:23]
	v_cmp_ne_u32_e64 s[8:9], 1, v4
	v_cndmask_b32_e64 v4, 0, 1, s[40:41]
	s_andn2_b64 vcc, exec, s[22:23]
	v_cmp_ne_u32_e64 s[6:7], 1, v4
	s_cbranch_vccnz .LBB0_1226
	s_and_b64 vcc, exec, s[6:7]
	s_mov_b64 s[48:49], -1
	s_cbranch_vccnz .LBB0_1223
	v_mfma_f32_16x16x32_bf16 v[10:13], v[142:145], v[174:177], v[10:13]
	s_mov_b64 s[48:49], 0
	v_mfma_f32_16x16x32_bf16 v[6:9], v[150:153], v[174:177], v[6:9]
	v_mfma_f32_16x16x32_bf16 v[10:13], v[146:149], v[178:181], v[10:13]
	v_mfma_f32_16x16x32_bf16 v[6:9], v[154:157], v[178:181], v[6:9]

; #define PG8_STAGEX(b, gbase) do { if constexpr (XR) { if (lane < 16) __builtin_amdgcn_global_load_lds((const unsigned*)((const char*)(gbase) + voffX), (PG8_LAS unsigned*)(lds + XR_OFF + (b) * 2048 + wid * 256), 16, 0, 0); } } while (0)
; #define PG8_LDX(b) do { if constexpr (XR) { _Pragma("unroll") for (int k = 0; k < 2; ++k) Ax_[k] = *(const PG8_LAS bf16x8*)(lds + XR_OFF + (b) * 2048 + aoffx + k * 1024); } } while (0)
; #define PG8_MMAX() do { if constexpr (XR) { if (hasx) { __builtin_amdgcn_s_setprio(1); if (wr == 0) PG8_MMAX_(B0); else PG8_MMAX_(B1); __builtin_amdgcn_s_setprio(0); } } } while (0)
; #define PG8_WAIT_LOOP() do { if constexpr (XR) PG8_WAIT_V(9); else PG8_WAIT_V(8); } while (0)
; #define PG8_STAGE(bufoff, gbase, voff) do { _Pragma("unroll") for (int _i = 0; _i < 2; ++_i) \
;         __builtin_amdgcn_global_load_lds((const unsigned*)((const char*)(gbase) + (voff)[_i]), (PG8_LAS unsigned*)(lds + (bufoff) + ldsw + _i * 8192), 16, 0, 0); } while (0)
; #define PG8_LDA(dst, b, h) do { _Pragma("unroll") for (int m = 0; m < 4; ++m) _Pragma("unroll") for (int k = 0; k < 2; ++k) dst[m][k] = *(const PG8_LAS bf16x8*)(lds + PG8_SA(b, h) + aoff + m * 2048 + k * 1024); } while (0)
; #define PG8_BAR __builtin_amdgcn_s_barrier()
; template <class Epi, class Sched, bool ALIGN_EPI = false, bool SP2 = false, bool DRAIN = true, bool XR = false>
; __device__ __forceinline__ void gemm_phase(PG8_LAS unsigned char* lds, const Gemm g, const Sched& S, const Epi& E) {
;     ...
;             const char* a1 = cA + PG8_KOA(t) + kstep;
;             const char* a2 = last ? nA + ka0 : cA + PG8_KOA(t + 2); const char* b2 = last ? nB + kb0 : cB + PG8_KOB(t + 2);
;             const char* x2 = XR ? (last ? nX + kx0 : cX + PG8_KOX(t + 2)) : nullptr; const char* x3 = XR ? x2 + kstep : nullptr;
;             const char* a3 = a2 + kstep; const char* b3 = b2 + kstep;
;             if (last && has_next) S.a_ready(nxt);
;             if constexpr (SP2) {
;             PG8_LDB(B0, 0, 0); PG8_LDB(B1, 0, 1); PG8_SCHED; PG8_LDA(At, 0, 0); PG8_LDX(0); PG8_STAGE(PG8_SA(1, 1), a1 + hstepA, voffA);
;             PG8_WAIT_LOOP(); PG8_WAIT_L(0); PG8_BAR; PG8_MMA(0, 0, At, B0); PG8_MMA(0, 1, At, B1); PG8_MMAX(); PG8_BAR; PG8_SCHED;
;             PG8_LDA(At, 0, 1); PG8_STAGE(PG8_SB(0, 0), b2, voffB); PG8_STAGE(PG8_SB(0, 1), b2 + hstep, voffB); PG8_STAGE(PG8_SA(0, 0), a2, voffA); PG8_STAGEX(0, x2);
.LBB0_1225:
.LBB0_1226:
	s_barrier
	s_add_i32 s89, s50, 2
	s_and_b32 s48, s89, s82
	s_lshr_b32 s84, s48, 2
	s_lshl_b32 s36, s48, 7
	s_lshl_b64 vcc, s[84:85], 9
	s_and_b32 s36, s36, 0x100
	s_add_u32 s49, s18, vcc_lo
	s_addc_u32 s51, s19, vcc_hi
	s_add_u32 s36, s49, s36
	s_mov_b32 s49, s85
	s_addc_u32 s51, s51, 0
	s_lshl_b64 s[48:49], s[48:49], 7
	s_add_u32 vcc_lo, s14, s48
	s_addc_u32 vcc_hi, s15, s49
	s_add_u32 s58, s16, s48
	s_addc_u32 s59, s17, s49
	s_cmp_eq_u32 s37, s50
	s_cselect_b32 s49, s43, s51
	s_cselect_b32 s48, s42, s36
	s_cselect_b32 s51, s97, s59
	s_cselect_b32 s50, s90, s58
	s_cselect_b32 vcc_hi, s45, vcc_hi
	s_cselect_b32 vcc_lo, s44, vcc_lo
	s_mov_b32 m0, s65
	v_lshl_add_u64 v[224:225], vcc, 0, v[216:217]
	v_lshl_add_u64 v[226:227], vcc, 0, v[220:221]
	s_add_u32 vcc_lo, vcc_lo, s10
	ds_read_b128 v[198:201], v251 offset:16384
	ds_read_b128 v[202:205], v251 offset:17408
	ds_read_b128 v[190:193], v251 offset:18432
	ds_read_b128 v[194:197], v251 offset:19456
	ds_read_b128 v[182:185], v251 offset:20480
	ds_read_b128 v[186:189], v251 offset:21504
	ds_read_b128 v[174:177], v251 offset:22528
	ds_read_b128 v[178:181], v251 offset:23552
	global_load_lds_dwordx4 v[224:225], off
	s_mov_b32 m0, s67
	s_addc_u32 vcc_hi, vcc_hi, s11
	global_load_lds_dwordx4 v[226:227], off
	v_lshl_add_u64 v[228:229], vcc, 0, v[216:217]
	s_mov_b32 m0, s68
	v_lshl_add_u64 v[230:231], vcc, 0, v[220:221]
	global_load_lds_dwordx4 v216, vcc
	s_mov_b32 m0, s69
	v_lshl_add_u64 v[232:233], s[48:49], 0, v[214:215]
	global_load_lds_dwordx4 v220, vcc
	s_mov_b32 m0, s64
	v_lshl_add_u64 v[234:235], s[48:49], 0, v[218:219]
	global_load_lds_dwordx4 v214, s[48:49]
	s_mov_b32 m0, s70
	v_lshl_add_u64 v[4:5], s[50:51], 0, v[222:223]
	global_load_lds_dwordx4 v218, s[48:49]
	s_and_saveexec_b64 s[50:51], s[2:3]
	s_cbranch_execz .LBB0_1228
	s_add_i32 s36, s57, 0
	s_add_i32 m0, s36, 0x22400
	s_nop 0
	global_load_lds_dwordx4 v[4:5], off
; #define PG8_LDX(b) do { if constexpr (XR) { _Pragma("unroll") for (int k = 0; k < 2; ++k) Ax_[k] = *(const PG8_LAS bf16x8*)(lds + XR_OFF + (b) * 2048 + aoffx + k * 1024); } } while (0)
; #define PG8_MMAX() do { if constexpr (XR) { if (hasx) { __builtin_amdgcn_s_setprio(1); if (wr == 0) PG8_MMAX_(B0); else PG8_MMAX_(B1); __builtin_amdgcn_s_setprio(0); } } } while (0)
; #define PG8_WAIT_LOOP() do { if constexpr (XR) PG8_WAIT_V(9); else PG8_WAIT_V(8); } while (0)
; #define PG8_STAGE(bufoff, gbase, voff) do { _Pragma("unroll") for (int _i = 0; _i < 2; ++_i) \
;         __builtin_amdgcn_global_load_lds((const unsigned*)((const char*)(gbase) + (voff)[_i]), (PG8_LAS unsigned*)(lds + (bufoff) + ldsw + _i * 8192), 16, 0, 0); } while (0)
; #define PG8_LDA(dst, b, h) do { _Pragma("unroll") for (int m = 0; m < 4; ++m) _Pragma("unroll") for (int k = 0; k < 2; ++k) dst[m][k] = *(const PG8_LAS bf16x8*)(lds + PG8_SA(b, h) + aoff + m * 2048 + k * 1024); } while (0)
; #define PG8_LDB(dst, b, h) do { _Pragma("unroll") for (int n = 0; n < 2; ++n) _Pragma("unroll") for (int k = 0; k < 2; ++k) dst[n][k] = *(const PG8_LAS bf16x8*)(lds + PG8_SB(b, h) + boff + n * 2048 + k * 1024); } while (0)
; #define PG8_MMA(ai, bj, At, Bt) do { __builtin_amdgcn_s_setprio(1); _Pragma("unroll") for (int m = 0; m < 4; ++m) _Pragma("unroll") for (int n = 0; n < 2; ++n) _Pragma("unroll") for (int k = 0; k < 2; ++k) \
;         acc[ai][bj][m][n] = __builtin_amdgcn_mfma_f32_16x16x32_bf16(Bt[n][k], At[m][k], acc[ai][bj][m][n], 0, 0, 0); __builtin_amdgcn_s_setprio(0); } while (0)
; #define PG8_WAIT_L(n) asm volatile("s_waitcnt lgkmcnt(" #n ")" ::: "memory")
; #define PG8_BAR __builtin_amdgcn_s_barrier()
; #define PG8_SCHED __builtin_amdgcn_sched_barrier(0)
; template <class Epi, class Sched, bool ALIGN_EPI = false, bool SP2 = false, bool DRAIN = true, bool XR = false>
; __device__ __forceinline__ void gemm_phase(PG8_LAS unsigned char* lds, const Gemm g, const Sched& S, const Epi& E) {
;     ...
;             PG8_WAIT_LOOP(); PG8_WAIT_L(0); PG8_BAR; PG8_MMA(1, 0, At, B0); PG8_MMA(1, 1, At, B1); PG8_BAR; PG8_SCHED;
;             PG8_LDB(B0, 1, 0); PG8_LDB(B1, 1, 1); PG8_SCHED; PG8_LDA(At, 1, 0); PG8_LDX(1); PG8_STAGE(PG8_SA(0, 1), a2 + hstepA, voffA);
;             PG8_WAIT_LOOP(); PG8_WAIT_L(0); PG8_BAR; PG8_MMA(0, 0, At, B0); PG8_MMA(0, 1, At, B1); PG8_MMAX(); PG8_BAR; PG8_SCHED;
.LBB0_1228:
	s_or_b64 exec, exec, s[50:51]
	s_waitcnt vmcnt(9)
	s_waitcnt lgkmcnt(0)
	s_barrier
	v_mfma_f32_16x16x32_bf16 v[74:77], v[158:161], v[198:201], v[74:77]
	v_mfma_f32_16x16x32_bf16 v[70:73], v[166:169], v[198:201], v[70:73]
	v_mfma_f32_16x16x32_bf16 v[66:69], v[158:161], v[190:193], v[66:69]
	v_mfma_f32_16x16x32_bf16 v[62:65], v[166:169], v[190:193], v[62:65]
	v_mfma_f32_16x16x32_bf16 v[58:61], v[158:161], v[182:185], v[58:61]
	v_mfma_f32_16x16x32_bf16 v[54:57], v[166:169], v[182:185], v[54:57]
	v_mfma_f32_16x16x32_bf16 v[50:53], v[158:161], v[174:177], v[50:53]
	v_mfma_f32_16x16x32_bf16 v[46:49], v[166:169], v[174:177], v[46:49]
	v_mfma_f32_16x16x32_bf16 v[74:77], v[162:165], v[202:205], v[74:77]
	v_mfma_f32_16x16x32_bf16 v[70:73], v[170:173], v[202:205], v[70:73]
	v_mfma_f32_16x16x32_bf16 v[66:69], v[162:165], v[194:197], v[66:69]
	v_mfma_f32_16x16x32_bf16 v[62:65], v[170:173], v[194:197], v[62:65]
	v_mfma_f32_16x16x32_bf16 v[58:61], v[162:165], v[186:189], v[58:61]
	v_mfma_f32_16x16x32_bf16 v[54:57], v[170:173], v[186:189], v[54:57]
	v_mfma_f32_16x16x32_bf16 v[50:53], v[162:165], v[178:181], v[50:53]
	v_mfma_f32_16x16x32_bf16 v[46:49], v[170:173], v[178:181], v[46:49]
	v_mfma_f32_16x16x32_bf16 v[42:45], v[142:145], v[198:201], v[42:45]
	v_mfma_f32_16x16x32_bf16 v[38:41], v[150:153], v[198:201], v[38:41]
	v_mfma_f32_16x16x32_bf16 v[34:37], v[142:145], v[190:193], v[34:37]
	v_mfma_f32_16x16x32_bf16 v[30:33], v[150:153], v[190:193], v[30:33]
	v_mfma_f32_16x16x32_bf16 v[26:29], v[142:145], v[182:185], v[26:29]
	v_mfma_f32_16x16x32_bf16 v[22:25], v[150:153], v[182:185], v[22:25]
	v_mfma_f32_16x16x32_bf16 v[18:21], v[142:145], v[174:177], v[18:21]
	v_mfma_f32_16x16x32_bf16 v[14:17], v[150:153], v[174:177], v[14:17]
	v_mfma_f32_16x16x32_bf16 v[42:45], v[146:149], v[202:205], v[42:45]
	v_mfma_f32_16x16x32_bf16 v[38:41], v[154:157], v[202:205], v[38:41]
	v_mfma_f32_16x16x32_bf16 v[34:37], v[146:149], v[194:197], v[34:37]
	v_mfma_f32_16x16x32_bf16 v[30:33], v[154:157], v[194:197], v[30:33]
	v_mfma_f32_16x16x32_bf16 v[26:29], v[146:149], v[186:189], v[26:29]
	v_mfma_f32_16x16x32_bf16 v[22:25], v[154:157], v[186:189], v[22:25]
	v_mfma_f32_16x16x32_bf16 v[18:21], v[146:149], v[178:181], v[18:21]
	v_mfma_f32_16x16x32_bf16 v[14:17], v[154:157], v[178:181], v[14:17]
	s_barrier
	v_add_u32_e32 v142, 0x18000, v250
	v_add_u32_e32 v154, 0x1c000, v250
	ds_read_b128 v[158:161], v142
	ds_read_b128 v[162:165], v142 offset:1024
	ds_read_b128 v[166:169], v142 offset:2048
	ds_read_b128 v[170:173], v142 offset:3072
	ds_read_b128 v[142:145], v154
	ds_read_b128 v[146:149], v154 offset:1024
	ds_read_b128 v[150:153], v154 offset:2048
	ds_read_b128 v[154:157], v154 offset:3072
	s_add_u32 s48, s48, s10
	s_addc_u32 s49, s49, s11
	s_mov_b32 m0, s71
	v_add_u32_e32 v178, 0x22c00, v240
	ds_read_b128 v[182:185], v251 offset:32768
	ds_read_b128 v[186:189], v251 offset:33792
	ds_read_b128 v[190:193], v251 offset:34816
	ds_read_b128 v[194:197], v251 offset:35840
	ds_read_b128 v[198:201], v251 offset:36864
	ds_read_b128 v[202:205], v251 offset:37888
	ds_read_b128 v[242:245], v251 offset:38912
	ds_read_b128 v[206:209], v251 offset:39936
	ds_read_b128 v[174:177], v178
	ds_read_b128 v[178:181], v178 offset:1024
	global_load_lds_dwordx4 v214, s[48:49]
	s_mov_b32 m0, s72
	s_nop 0
	global_load_lds_dwordx4 v218, s[48:49]
	s_waitcnt vmcnt(9)
	s_waitcnt lgkmcnt(0)
	s_barrier
	v_mfma_f32_16x16x32_bf16 v[138:141], v[158:161], v[182:185], v[138:141]
	v_mfma_f32_16x16x32_bf16 v[134:137], v[166:169], v[182:185], v[134:137]
	v_mfma_f32_16x16x32_bf16 v[130:133], v[158:161], v[190:193], v[130:133]
	v_mfma_f32_16x16x32_bf16 v[126:129], v[166:169], v[190:193], v[126:129]
	v_mfma_f32_16x16x32_bf16 v[122:125], v[158:161], v[198:201], v[122:125]
	v_mfma_f32_16x16x32_bf16 v[118:121], v[166:169], v[198:201], v[118:121]
	v_mfma_f32_16x16x32_bf16 v[114:117], v[158:161], v[242:245], v[114:117]
	v_mfma_f32_16x16x32_bf16 v[110:113], v[166:169], v[242:245], v[110:113]
	v_mfma_f32_16x16x32_bf16 v[138:141], v[162:165], v[186:189], v[138:141]
	v_mfma_f32_16x16x32_bf16 v[134:137], v[170:173], v[186:189], v[134:137]
	v_mfma_f32_16x16x32_bf16 v[130:133], v[162:165], v[194:197], v[130:133]
	v_mfma_f32_16x16x32_bf16 v[126:129], v[170:173], v[194:197], v[126:129]
	v_mfma_f32_16x16x32_bf16 v[122:125], v[162:165], v[202:205], v[122:125]
	v_mfma_f32_16x16x32_bf16 v[118:121], v[170:173], v[202:205], v[118:121]
	v_mfma_f32_16x16x32_bf16 v[114:117], v[162:165], v[206:209], v[114:117]
	v_mfma_f32_16x16x32_bf16 v[110:113], v[170:173], v[206:209], v[110:113]
	v_mfma_f32_16x16x32_bf16 v[106:109], v[142:145], v[182:185], v[106:109]
	v_mfma_f32_16x16x32_bf16 v[102:105], v[150:153], v[182:185], v[102:105]
	v_mfma_f32_16x16x32_bf16 v[98:101], v[142:145], v[190:193], v[98:101]
	v_mfma_f32_16x16x32_bf16 v[94:97], v[150:153], v[190:193], v[94:97]
	v_mfma_f32_16x16x32_bf16 v[90:93], v[142:145], v[198:201], v[90:93]
	v_mfma_f32_16x16x32_bf16 v[86:89], v[150:153], v[198:201], v[86:89]
	v_mfma_f32_16x16x32_bf16 v[82:85], v[142:145], v[242:245], v[82:85]
	v_mfma_f32_16x16x32_bf16 v[78:81], v[150:153], v[242:245], v[78:81]
	v_mfma_f32_16x16x32_bf16 v[106:109], v[146:149], v[186:189], v[106:109]
	v_mfma_f32_16x16x32_bf16 v[102:105], v[154:157], v[186:189], v[102:105]
	v_mfma_f32_16x16x32_bf16 v[98:101], v[146:149], v[194:197], v[98:101]
	v_mfma_f32_16x16x32_bf16 v[94:97], v[154:157], v[194:197], v[94:97]
	v_mfma_f32_16x16x32_bf16 v[90:93], v[146:149], v[202:205], v[90:93]
	v_mfma_f32_16x16x32_bf16 v[86:89], v[154:157], v[202:205], v[86:89]
	v_mfma_f32_16x16x32_bf16 v[82:85], v[146:149], v[206:209], v[82:85]
	v_mfma_f32_16x16x32_bf16 v[78:81], v[154:157], v[206:209], v[78:81]
	s_and_b64 vcc, exec, s[8:9]
	s_cbranch_vccnz .LBB0_1234
	s_and_b64 vcc, exec, s[6:7]
	s_mov_b64 s[6:7], -1
	s_cbranch_vccnz .LBB0_1231
	v_mfma_f32_16x16x32_bf16 v[10:13], v[142:145], v[174:177], v[10:13]
	s_mov_b64 s[6:7], 0
	v_mfma_f32_16x16x32_bf16 v[6:9], v[150:153], v[174:177], v[6:9]
	v_mfma_f32_16x16x32_bf16 v[10:13], v[146:149], v[178:181], v[10:13]
	v_mfma_f32_16x16x32_bf16 v[6:9], v[154:157], v[178:181], v[6:9]

; #define PG8_STAGEX(b, gbase) do { if constexpr (XR) { if (lane < 16) __builtin_amdgcn_global_load_lds((const unsigned*)((const char*)(gbase) + voffX), (PG8_LAS unsigned*)(lds + XR_OFF + (b) * 2048 + wid * 256), 16, 0, 0); } } while (0)
; #define PG8_MMAX() do { if constexpr (XR) { if (hasx) { __builtin_amdgcn_s_setprio(1); if (wr == 0) PG8_MMAX_(B0); else PG8_MMAX_(B1); __builtin_amdgcn_s_setprio(0); } } } while (0)
; #define PG8_WAIT_LOOP() do { if constexpr (XR) PG8_WAIT_V(9); else PG8_WAIT_V(8); } while (0)
; #define PG8_STAGE(bufoff, gbase, voff) do { _Pragma("unroll") for (int _i = 0; _i < 2; ++_i) \
;         __builtin_amdgcn_global_load_lds((const unsigned*)((const char*)(gbase) + (voff)[_i]), (PG8_LAS unsigned*)(lds + (bufoff) + ldsw + _i * 8192), 16, 0, 0); } while (0)
; #define PG8_LDA(dst, b, h) do { _Pragma("unroll") for (int m = 0; m < 4; ++m) _Pragma("unroll") for (int k = 0; k < 2; ++k) dst[m][k] = *(const PG8_LAS bf16x8*)(lds + PG8_SA(b, h) + aoff + m * 2048 + k * 1024); } while (0)
; #define PG8_MMA(ai, bj, At, Bt) do { __builtin_amdgcn_s_setprio(1); _Pragma("unroll") for (int m = 0; m < 4; ++m) _Pragma("unroll") for (int n = 0; n < 2; ++n) _Pragma("unroll") for (int k = 0; k < 2; ++k) \
;         acc[ai][bj][m][n] = __builtin_amdgcn_mfma_f32_16x16x32_bf16(Bt[n][k], At[m][k], acc[ai][bj][m][n], 0, 0, 0); __builtin_amdgcn_s_setprio(0); } while (0)
; #define PG8_WAIT_L(n) asm volatile("s_waitcnt lgkmcnt(" #n ")" ::: "memory")
; #define PG8_BAR __builtin_amdgcn_s_barrier()
; #define PG8_SCHED __builtin_amdgcn_sched_barrier(0)
; template <class Epi, class Sched, bool ALIGN_EPI = false, bool SP2 = false, bool DRAIN = true, bool XR = false>
; __device__ __forceinline__ void gemm_phase(PG8_LAS unsigned char* lds, const Gemm g, const Sched& S, const Epi& E) {
;     ...
;             PG8_WAIT_LOOP(); PG8_WAIT_L(0); PG8_BAR; PG8_MMA(0, 0, At, B0); PG8_MMA(0, 1, At, B1); PG8_MMAX(); PG8_BAR; PG8_SCHED;
;             PG8_LDA(At, 1, 1); PG8_STAGE(PG8_SB(1, 0), b3, voffB); PG8_STAGE(PG8_SB(1, 1), b3 + hstep, voffB); PG8_STAGE(PG8_SA(1, 0), a3, voffA); PG8_STAGEX(1, x3);
.LBB0_1233:
.LBB0_1234:
	s_barrier
	s_mov_b32 m0, s74
	v_lshl_add_u64 v[206:207], v[224:225], 0, s[86:87]
	ds_read_b128 v[198:201], v251 offset:49152
	ds_read_b128 v[202:205], v251 offset:50176
	ds_read_b128 v[190:193], v251 offset:51200
	ds_read_b128 v[194:197], v251 offset:52224
	ds_read_b128 v[182:185], v251 offset:53248
	ds_read_b128 v[186:189], v251 offset:54272
	ds_read_b128 v[174:177], v251 offset:55296
	ds_read_b128 v[178:181], v251 offset:56320
	global_load_lds_dwordx4 v[206:207], off
	v_lshl_add_u64 v[206:207], v[226:227], 0, s[86:87]
	s_mov_b32 m0, s75
	s_nop 0
	global_load_lds_dwordx4 v[206:207], off
	v_lshl_add_u64 v[206:207], v[228:229], 0, s[86:87]
	s_mov_b32 m0, s78
	s_nop 0
	global_load_lds_dwordx4 v[206:207], off
	v_lshl_add_u64 v[206:207], v[230:231], 0, s[86:87]
	s_mov_b32 m0, s79
	s_nop 0
	global_load_lds_dwordx4 v[206:207], off
	v_lshl_add_u64 v[206:207], v[232:233], 0, s[86:87]
	s_mov_b32 m0, s76
	s_nop 0
	global_load_lds_dwordx4 v[206:207], off
	v_lshl_add_u64 v[206:207], v[234:235], 0, s[86:87]
	s_mov_b32 m0, s77
	s_nop 0
	global_load_lds_dwordx4 v[206:207], off
	s_and_saveexec_b64 s[6:7], s[2:3]
	s_cbranch_execz .LBB0_1236
	s_add_i32 s8, s57, 0
	v_lshl_add_u64 v[4:5], v[4:5], 0, s[86:87]
	s_add_i32 m0, s8, 0x22c00
	s_nop 0
	global_load_lds_dwordx4 v[4:5], off

; #define PG8_LDX(b) do { if constexpr (XR) { _Pragma("unroll") for (int k = 0; k < 2; ++k) Ax_[k] = *(const PG8_LAS bf16x8*)(lds + XR_OFF + (b) * 2048 + aoffx + k * 1024); } } while (0)
; #define PG8_MMAX() do { if constexpr (XR) { if (hasx) { __builtin_amdgcn_s_setprio(1); if (wr == 0) PG8_MMAX_(B0); else PG8_MMAX_(B1); __builtin_amdgcn_s_setprio(0); } } } while (0)
; #define PG8_WAIT_LOOP() do { if constexpr (XR) PG8_WAIT_V(9); else PG8_WAIT_V(8); } while (0)
; #define PG8_STAGE(bufoff, gbase, voff) do { _Pragma("unroll") for (int _i = 0; _i < 2; ++_i) \
;         __builtin_amdgcn_global_load_lds((const unsigned*)((const char*)(gbase) + (voff)[_i]), (PG8_LAS unsigned*)(lds + (bufoff) + ldsw + _i * 8192), 16, 0, 0); } while (0)
; #define PG8_LDA(dst, b, h) do { _Pragma("unroll") for (int m = 0; m < 4; ++m) _Pragma("unroll") for (int k = 0; k < 2; ++k) dst[m][k] = *(const PG8_LAS bf16x8*)(lds + PG8_SA(b, h) + aoff + m * 2048 + k * 1024); } while (0)
; #define PG8_LDB(dst, b, h) do { _Pragma("unroll") for (int n = 0; n < 2; ++n) _Pragma("unroll") for (int k = 0; k < 2; ++k) dst[n][k] = *(const PG8_LAS bf16x8*)(lds + PG8_SB(b, h) + boff + n * 2048 + k * 1024); } while (0)
; #define PG8_MMA(ai, bj, At, Bt) do { __builtin_amdgcn_s_setprio(1); _Pragma("unroll") for (int m = 0; m < 4; ++m) _Pragma("unroll") for (int n = 0; n < 2; ++n) _Pragma("unroll") for (int k = 0; k < 2; ++k) \
;         acc[ai][bj][m][n] = __builtin_amdgcn_mfma_f32_16x16x32_bf16(Bt[n][k], At[m][k], acc[ai][bj][m][n], 0, 0, 0); __builtin_amdgcn_s_setprio(0); } while (0)
; #define PG8_WAIT_L(n) asm volatile("s_waitcnt lgkmcnt(" #n ")" ::: "memory")
; #define PG8_BAR __builtin_amdgcn_s_barrier()
; #define PG8_SCHED __builtin_amdgcn_sched_barrier(0)
; template <class Epi, class Sched, bool ALIGN_EPI = false, bool SP2 = false, bool DRAIN = true, bool XR = false>
; __device__ __forceinline__ void gemm_phase(PG8_LAS unsigned char* lds, const Gemm g, const Sched& S, const Epi& E) {
;     ...
;             PG8_LDB(B0, 0, 0); PG8_LDB(B1, 0, 1); PG8_SCHED; PG8_LDA(At, 0, 0); PG8_LDX(0); PG8_STAGE(PG8_SA(1, 1), a1 + hstepA, voffA);
;             PG8_WAIT_LOOP(); PG8_WAIT_L(0); PG8_BAR; PG8_MMA(0, 0, At, B0); PG8_MMA(0, 1, At, B1); PG8_MMAX(); PG8_BAR; PG8_SCHED;
.LBB0_1359:
	v_add_u32_e32 v2, 0x10000, v248
	s_add_i32 s4, s90, -2
	ds_read_b128 v[158:161], v2
	ds_read_b128 v[162:165], v2 offset:1024
	ds_read_b128 v[166:169], v2 offset:2048
	ds_read_b128 v[170:173], v2 offset:3072
	v_add_u32_e32 v2, 0x14000, v248
	s_and_b32 s6, s4, s73
	ds_read_b128 v[142:145], v2
	ds_read_b128 v[146:149], v2 offset:1024
	ds_read_b128 v[150:153], v2 offset:2048
	ds_read_b128 v[154:157], v2 offset:3072
	s_lshr_b32 s84, s6, 2
	s_lshl_b32 s6, s6, 7
	s_lshl_b64 s[4:5], s[84:85], 9
	s_and_b32 s6, s6, 0x100
	s_add_u32 s4, s56, s4
	s_addc_u32 s5, s57, s5
	s_add_u32 s4, s4, s6
	s_addc_u32 s5, s5, 0
	s_add_u32 s4, s4, s28
	s_addc_u32 s5, s5, s29
	v_lshl_add_u64 v[4:5], s[4:5], 0, v[220:221]
	v_add_u32_e32 v2, 0x22400, v250
	v_lshl_add_u64 v[4:5], v[4:5], 0, s[86:87]
	s_add_i32 m0, s13, 0xc000
	ds_read_b128 v[182:185], v249
	ds_read_b128 v[186:189], v249 offset:1024
	ds_read_b128 v[190:193], v249 offset:2048
	ds_read_b128 v[194:197], v249 offset:3072
	ds_read_b128 v[198:201], v249 offset:4096
	ds_read_b128 v[202:205], v249 offset:5120
	ds_read_b128 v[206:209], v249 offset:6144
	ds_read_b128 v[224:227], v249 offset:7168
	ds_read_b128 v[174:177], v2
	ds_read_b128 v[178:181], v2 offset:1024
	global_load_lds_dwordx4 v[4:5], off
	v_lshl_add_u64 v[4:5], s[4:5], 0, v[216:217]
	v_lshl_add_u64 v[4:5], v[4:5], 0, s[86:87]
	s_add_i32 m0, s13, 0xe000
	s_nop 0
	global_load_lds_dwordx4 v[4:5], off
	s_waitcnt vmcnt(9)
	s_waitcnt lgkmcnt(0)
	s_barrier
	v_mfma_f32_16x16x32_bf16 v[138:141], v[158:161], v[182:185], v[138:141]
	v_mfma_f32_16x16x32_bf16 v[134:137], v[166:169], v[182:185], v[134:137]
	v_mfma_f32_16x16x32_bf16 v[122:125], v[158:161], v[190:193], v[122:125]
	v_mfma_f32_16x16x32_bf16 v[118:121], v[166:169], v[190:193], v[118:121]
	v_mfma_f32_16x16x32_bf16 v[106:109], v[158:161], v[198:201], v[106:109]
	v_mfma_f32_16x16x32_bf16 v[102:105], v[166:169], v[198:201], v[102:105]
	v_mfma_f32_16x16x32_bf16 v[90:93], v[158:161], v[206:209], v[90:93]
	v_mfma_f32_16x16x32_bf16 v[86:89], v[166:169], v[206:209], v[86:89]
	v_mfma_f32_16x16x32_bf16 v[138:141], v[162:165], v[186:189], v[138:141]
	v_mfma_f32_16x16x32_bf16 v[134:137], v[170:173], v[186:189], v[134:137]
	v_mfma_f32_16x16x32_bf16 v[122:125], v[162:165], v[194:197], v[122:125]
	v_mfma_f32_16x16x32_bf16 v[118:121], v[170:173], v[194:197], v[118:121]
	v_mfma_f32_16x16x32_bf16 v[106:109], v[162:165], v[202:205], v[106:109]
	v_mfma_f32_16x16x32_bf16 v[102:105], v[170:173], v[202:205], v[102:105]
	v_mfma_f32_16x16x32_bf16 v[90:93], v[162:165], v[224:227], v[90:93]
	v_mfma_f32_16x16x32_bf16 v[86:89], v[170:173], v[224:227], v[86:89]
	v_mfma_f32_16x16x32_bf16 v[130:133], v[142:145], v[182:185], v[130:133]
	v_mfma_f32_16x16x32_bf16 v[126:129], v[150:153], v[182:185], v[126:129]
	v_mfma_f32_16x16x32_bf16 v[114:117], v[142:145], v[190:193], v[114:117]
	v_mfma_f32_16x16x32_bf16 v[110:113], v[150:153], v[190:193], v[110:113]
	v_mfma_f32_16x16x32_bf16 v[98:101], v[142:145], v[198:201], v[98:101]
	v_mfma_f32_16x16x32_bf16 v[94:97], v[150:153], v[198:201], v[94:97]
	v_mfma_f32_16x16x32_bf16 v[82:85], v[142:145], v[206:209], v[82:85]
	v_mfma_f32_16x16x32_bf16 v[78:81], v[150:153], v[206:209], v[78:81]
	v_mfma_f32_16x16x32_bf16 v[130:133], v[146:149], v[186:189], v[130:133]
	v_mfma_f32_16x16x32_bf16 v[126:129], v[154:157], v[186:189], v[126:129]
	v_mfma_f32_16x16x32_bf16 v[114:117], v[146:149], v[194:197], v[114:117]
	v_mfma_f32_16x16x32_bf16 v[110:113], v[154:157], v[194:197], v[110:113]
	v_mfma_f32_16x16x32_bf16 v[98:101], v[146:149], v[202:205], v[98:101]
	v_mfma_f32_16x16x32_bf16 v[94:97], v[154:157], v[202:205], v[94:97]
	v_mfma_f32_16x16x32_bf16 v[82:85], v[146:149], v[224:227], v[82:85]
	v_mfma_f32_16x16x32_bf16 v[78:81], v[154:157], v[224:227], v[78:81]
	v_cndmask_b32_e64 v2, 0, 1, s[46:47]
	v_cmp_ne_u32_e64 s[6:7], 1, v2
	v_cndmask_b32_e64 v2, 0, 1, s[44:45]
	s_andn2_b64 vcc, exec, s[46:47]
	v_cmp_ne_u32_e64 s[4:5], 1, v2
	s_cbranch_vccnz .LBB0_1365
	s_and_b64 vcc, exec, s[4:5]
	s_mov_b64 s[60:61], -1
	s_cbranch_vccnz .LBB0_1362
	v_mfma_f32_16x16x32_bf16 v[10:13], v[142:145], v[174:177], v[10:13]
	s_mov_b64 s[60:61], 0
	v_mfma_f32_16x16x32_bf16 v[6:9], v[150:153], v[174:177], v[6:9]
	v_mfma_f32_16x16x32_bf16 v[10:13], v[146:149], v[178:181], v[10:13]
	v_mfma_f32_16x16x32_bf16 v[6:9], v[154:157], v[178:181], v[6:9]

; #define PG8_STAGEX(b, gbase) do { if constexpr (XR) { if (lane < 16) __builtin_amdgcn_global_load_lds((const unsigned*)((const char*)(gbase) + voffX), (PG8_LAS unsigned*)(lds + XR_OFF + (b) * 2048 + wid * 256), 16, 0, 0); } } while (0)
; #define PG8_LDX(b) do { if constexpr (XR) { _Pragma("unroll") for (int k = 0; k < 2; ++k) Ax_[k] = *(const PG8_LAS bf16x8*)(lds + XR_OFF + (b) * 2048 + aoffx + k * 1024); } } while (0)
; #define PG8_MMAX() do { if constexpr (XR) { if (hasx) { __builtin_amdgcn_s_setprio(1); if (wr == 0) PG8_MMAX_(B0); else PG8_MMAX_(B1); __builtin_amdgcn_s_setprio(0); } } } while (0)
; #define PG8_WAIT_LOOP() do { if constexpr (XR) PG8_WAIT_V(9); else PG8_WAIT_V(8); } while (0)
; #define PG8_STAGE(bufoff, gbase, voff) do { _Pragma("unroll") for (int _i = 0; _i < 2; ++_i) \
;         __builtin_amdgcn_global_load_lds((const unsigned*)((const char*)(gbase) + (voff)[_i]), (PG8_LAS unsigned*)(lds + (bufoff) + ldsw + _i * 8192), 16, 0, 0); } while (0)
; #define PG8_LDA(dst, b, h) do { _Pragma("unroll") for (int m = 0; m < 4; ++m) _Pragma("unroll") for (int k = 0; k < 2; ++k) dst[m][k] = *(const PG8_LAS bf16x8*)(lds + PG8_SA(b, h) + aoff + m * 2048 + k * 1024); } while (0)
; #define PG8_BAR __builtin_amdgcn_s_barrier()
; template <class Epi, class Sched, bool ALIGN_EPI = false, bool SP2 = false, bool DRAIN = true, bool XR = false>
; __device__ __forceinline__ void gemm_phase(PG8_LAS unsigned char* lds, const Gemm g, const Sched& S, const Epi& E) {
;     ...
;             const char* a1 = cA + PG8_KOA(t) + kstep;
;             const char* a2 = last ? nA + ka0 : cA + PG8_KOA(t + 2); const char* b2 = last ? nB + kb0 : cB + PG8_KOB(t + 2);
;             const char* x2 = XR ? (last ? nX + kx0 : cX + PG8_KOX(t + 2)) : nullptr; const char* x3 = XR ? x2 + kstep : nullptr;
;             const char* a3 = a2 + kstep; const char* b3 = b2 + kstep;
;             if (last && has_next) S.a_ready(nxt);
;             if constexpr (SP2) {
;             PG8_LDB(B0, 0, 0); PG8_LDB(B1, 0, 1); PG8_SCHED; PG8_LDA(At, 0, 0); PG8_LDX(0); PG8_STAGE(PG8_SA(1, 1), a1 + hstepA, voffA);
;             PG8_WAIT_LOOP(); PG8_WAIT_L(0); PG8_BAR; PG8_MMA(0, 0, At, B0); PG8_MMA(0, 1, At, B1); PG8_MMAX(); PG8_BAR; PG8_SCHED;
;             PG8_LDA(At, 0, 1); PG8_STAGE(PG8_SB(0, 0), b2, voffB); PG8_STAGE(PG8_SB(0, 1), b2 + hstep, voffB); PG8_STAGE(PG8_SA(0, 0), a2, voffA); PG8_STAGEX(0, x2);
.LBB0_1364:
.LBB0_1365:
	s_barrier
	s_and_b32 s8, s90, s73
	s_lshr_b32 s84, s8, 2
	s_lshl_b32 s9, s8, 7
	s_lshl_b64 s[20:21], s[84:85], 9
	s_and_b32 s9, s9, 0x100
	s_add_u32 s20, s56, s20
	s_addc_u32 s21, s57, s21
	s_add_u32 s20, s20, s9
	s_mov_b32 s9, s85
	s_addc_u32 s21, s21, 0
	s_lshl_b64 s[8:9], s[8:9], 7
	s_add_u32 s36, s54, s8
	s_addc_u32 s62, s55, s9
	s_add_u32 s8, s58, s8
	s_addc_u32 s9, s59, s9
	s_cmp_eq_u32 s65, s90
	s_cselect_b32 s61, s49, s21
	s_cselect_b32 s60, s48, s20
	s_cselect_b32 s9, s88, s9
	s_cselect_b32 s8, s89, s8
	s_cselect_b32 s21, s51, s62
	s_cselect_b32 s20, s50, s36
	s_mov_b32 m0, s14
	v_lshl_add_u64 v[224:225], s[20:21], 0, v[218:219]
	v_lshl_add_u64 v[226:227], s[20:21], 0, v[214:215]
	s_add_u32 s20, s20, s28
	ds_read_b128 v[198:201], v249 offset:16384
	ds_read_b128 v[202:205], v249 offset:17408
	ds_read_b128 v[190:193], v249 offset:18432
	ds_read_b128 v[194:197], v249 offset:19456
	ds_read_b128 v[182:185], v249 offset:20480
	ds_read_b128 v[186:189], v249 offset:21504
	ds_read_b128 v[174:177], v249 offset:22528
	ds_read_b128 v[178:181], v249 offset:23552
	global_load_lds_dwordx4 v[224:225], off
	s_mov_b32 m0, s15
	s_addc_u32 s21, s21, s29
	global_load_lds_dwordx4 v[226:227], off
	v_lshl_add_u64 v[228:229], s[20:21], 0, v[218:219]
	s_mov_b32 m0, s16
	v_lshl_add_u64 v[230:231], s[20:21], 0, v[214:215]
	global_load_lds_dwordx4 v218, s[20:21]
	s_mov_b32 m0, s17
	v_lshl_add_u64 v[232:233], s[60:61], 0, v[220:221]
	global_load_lds_dwordx4 v214, s[20:21]
	s_mov_b32 m0, s13
	v_lshl_add_u64 v[234:235], s[60:61], 0, v[216:217]
	global_load_lds_dwordx4 v220, s[60:61]
	s_mov_b32 m0, s18
	v_lshl_add_u64 v[4:5], s[8:9], 0, v[222:223]
	global_load_lds_dwordx4 v216, s[60:61]
	s_and_saveexec_b64 s[62:63], s[0:1]
	s_cbranch_execz .LBB0_1367
	s_add_i32 s8, s12, 0
	s_add_i32 m0, s8, 0x22400
	s_nop 0
	global_load_lds_dwordx4 v[4:5], off
; #define PG8_LDX(b) do { if constexpr (XR) { _Pragma("unroll") for (int k = 0; k < 2; ++k) Ax_[k] = *(const PG8_LAS bf16x8*)(lds + XR_OFF + (b) * 2048 + aoffx + k * 1024); } } while (0)
; #define PG8_MMAX() do { if constexpr (XR) { if (hasx) { __builtin_amdgcn_s_setprio(1); if (wr == 0) PG8_MMAX_(B0); else PG8_MMAX_(B1); __builtin_amdgcn_s_setprio(0); } } } while (0)
; #define PG8_WAIT_LOOP() do { if constexpr (XR) PG8_WAIT_V(9); else PG8_WAIT_V(8); } while (0)
; #define PG8_STAGE(bufoff, gbase, voff) do { _Pragma("unroll") for (int _i = 0; _i < 2; ++_i) \
;         __builtin_amdgcn_global_load_lds((const unsigned*)((const char*)(gbase) + (voff)[_i]), (PG8_LAS unsigned*)(lds + (bufoff) + ldsw + _i * 8192), 16, 0, 0); } while (0)
; #define PG8_LDA(dst, b, h) do { _Pragma("unroll") for (int m = 0; m < 4; ++m) _Pragma("unroll") for (int k = 0; k < 2; ++k) dst[m][k] = *(const PG8_LAS bf16x8*)(lds + PG8_SA(b, h) + aoff + m * 2048 + k * 1024); } while (0)
; #define PG8_LDB(dst, b, h) do { _Pragma("unroll") for (int n = 0; n < 2; ++n) _Pragma("unroll") for (int k = 0; k < 2; ++k) dst[n][k] = *(const PG8_LAS bf16x8*)(lds + PG8_SB(b, h) + boff + n * 2048 + k * 1024); } while (0)
; #define PG8_MMA(ai, bj, At, Bt) do { __builtin_amdgcn_s_setprio(1); _Pragma("unroll") for (int m = 0; m < 4; ++m) _Pragma("unroll") for (int n = 0; n < 2; ++n) _Pragma("unroll") for (int k = 0; k < 2; ++k) \
;         acc[ai][bj][m][n] = __builtin_amdgcn_mfma_f32_16x16x32_bf16(Bt[n][k], At[m][k], acc[ai][bj][m][n], 0, 0, 0); __builtin_amdgcn_s_setprio(0); } while (0)
; #define PG8_WAIT_L(n) asm volatile("s_waitcnt lgkmcnt(" #n ")" ::: "memory")
; #define PG8_BAR __builtin_amdgcn_s_barrier()
; #define PG8_SCHED __builtin_amdgcn_sched_barrier(0)
; template <class Epi, class Sched, bool ALIGN_EPI = false, bool SP2 = false, bool DRAIN = true, bool XR = false>
; __device__ __forceinline__ void gemm_phase(PG8_LAS unsigned char* lds, const Gemm g, const Sched& S, const Epi& E) {
;     ...
;             PG8_WAIT_LOOP(); PG8_WAIT_L(0); PG8_BAR; PG8_MMA(1, 0, At, B0); PG8_MMA(1, 1, At, B1); PG8_BAR; PG8_SCHED;
;             PG8_LDB(B0, 1, 0); PG8_LDB(B1, 1, 1); PG8_SCHED; PG8_LDA(At, 1, 0); PG8_LDX(1); PG8_STAGE(PG8_SA(0, 1), a2 + hstepA, voffA);
;             PG8_WAIT_LOOP(); PG8_WAIT_L(0); PG8_BAR; PG8_MMA(0, 0, At, B0); PG8_MMA(0, 1, At, B1); PG8_MMAX(); PG8_BAR; PG8_SCHED;
.LBB0_1367:
	s_or_b64 exec, exec, s[62:63]
	s_waitcnt vmcnt(9)
	s_waitcnt lgkmcnt(0)
	s_barrier
	v_mfma_f32_16x16x32_bf16 v[74:77], v[158:161], v[198:201], v[74:77]
	v_mfma_f32_16x16x32_bf16 v[70:73], v[166:169], v[198:201], v[70:73]
	v_mfma_f32_16x16x32_bf16 v[58:61], v[158:161], v[190:193], v[58:61]
	v_mfma_f32_16x16x32_bf16 v[54:57], v[166:169], v[190:193], v[54:57]
	v_mfma_f32_16x16x32_bf16 v[42:45], v[158:161], v[182:185], v[42:45]
	v_mfma_f32_16x16x32_bf16 v[38:41], v[166:169], v[182:185], v[38:41]
	v_mfma_f32_16x16x32_bf16 v[26:29], v[158:161], v[174:177], v[26:29]
	v_mfma_f32_16x16x32_bf16 v[22:25], v[166:169], v[174:177], v[22:25]
	v_mfma_f32_16x16x32_bf16 v[74:77], v[162:165], v[202:205], v[74:77]
	v_mfma_f32_16x16x32_bf16 v[70:73], v[170:173], v[202:205], v[70:73]
	v_mfma_f32_16x16x32_bf16 v[58:61], v[162:165], v[194:197], v[58:61]
	v_mfma_f32_16x16x32_bf16 v[54:57], v[170:173], v[194:197], v[54:57]
	v_mfma_f32_16x16x32_bf16 v[42:45], v[162:165], v[186:189], v[42:45]
	v_mfma_f32_16x16x32_bf16 v[38:41], v[170:173], v[186:189], v[38:41]
	v_mfma_f32_16x16x32_bf16 v[26:29], v[162:165], v[178:181], v[26:29]
	v_mfma_f32_16x16x32_bf16 v[22:25], v[170:173], v[178:181], v[22:25]
	v_mfma_f32_16x16x32_bf16 v[66:69], v[142:145], v[198:201], v[66:69]
	v_mfma_f32_16x16x32_bf16 v[62:65], v[150:153], v[198:201], v[62:65]
	v_mfma_f32_16x16x32_bf16 v[50:53], v[142:145], v[190:193], v[50:53]
	v_mfma_f32_16x16x32_bf16 v[46:49], v[150:153], v[190:193], v[46:49]
	v_mfma_f32_16x16x32_bf16 v[34:37], v[142:145], v[182:185], v[34:37]
	v_mfma_f32_16x16x32_bf16 v[30:33], v[150:153], v[182:185], v[30:33]
	v_mfma_f32_16x16x32_bf16 v[18:21], v[142:145], v[174:177], v[18:21]
	v_mfma_f32_16x16x32_bf16 v[14:17], v[150:153], v[174:177], v[14:17]
	v_mfma_f32_16x16x32_bf16 v[66:69], v[146:149], v[202:205], v[66:69]
	v_mfma_f32_16x16x32_bf16 v[62:65], v[154:157], v[202:205], v[62:65]
	v_mfma_f32_16x16x32_bf16 v[50:53], v[146:149], v[194:197], v[50:53]
	v_mfma_f32_16x16x32_bf16 v[46:49], v[154:157], v[194:197], v[46:49]
	v_mfma_f32_16x16x32_bf16 v[34:37], v[146:149], v[186:189], v[34:37]
	v_mfma_f32_16x16x32_bf16 v[30:33], v[154:157], v[186:189], v[30:33]
	v_mfma_f32_16x16x32_bf16 v[18:21], v[146:149], v[178:181], v[18:21]
	v_mfma_f32_16x16x32_bf16 v[14:17], v[154:157], v[178:181], v[14:17]
	s_barrier
	v_add_u32_e32 v2, 0x18000, v248
	ds_read_b128 v[158:161], v2
	ds_read_b128 v[162:165], v2 offset:1024
	ds_read_b128 v[166:169], v2 offset:2048
	ds_read_b128 v[170:173], v2 offset:3072
	v_add_u32_e32 v2, 0x1c000, v248
	ds_read_b128 v[142:145], v2
	ds_read_b128 v[146:149], v2 offset:1024
	ds_read_b128 v[150:153], v2 offset:2048
	ds_read_b128 v[154:157], v2 offset:3072
	s_add_u32 s8, s60, s28
	s_addc_u32 s9, s61, s29
	s_mov_b32 m0, s19
	v_add_u32_e32 v2, 0x22c00, v250
	ds_read_b128 v[182:185], v249 offset:32768
	ds_read_b128 v[186:189], v249 offset:33792
	ds_read_b128 v[190:193], v249 offset:34816
	ds_read_b128 v[194:197], v249 offset:35840
	ds_read_b128 v[198:201], v249 offset:36864
	ds_read_b128 v[202:205], v249 offset:37888
	ds_read_b128 v[206:209], v249 offset:38912
	ds_read_b128 v[242:245], v249 offset:39936
	ds_read_b128 v[174:177], v2
	ds_read_b128 v[178:181], v2 offset:1024
	global_load_lds_dwordx4 v220, s[8:9]
	s_mov_b32 m0, s22
	s_nop 0
	global_load_lds_dwordx4 v216, s[8:9]
	s_waitcnt vmcnt(9)
	s_waitcnt lgkmcnt(0)
	s_barrier
	v_mfma_f32_16x16x32_bf16 v[138:141], v[158:161], v[182:185], v[138:141]
	v_mfma_f32_16x16x32_bf16 v[134:137], v[166:169], v[182:185], v[134:137]
	v_mfma_f32_16x16x32_bf16 v[122:125], v[158:161], v[190:193], v[122:125]
	v_mfma_f32_16x16x32_bf16 v[118:121], v[166:169], v[190:193], v[118:121]
	v_mfma_f32_16x16x32_bf16 v[106:109], v[158:161], v[198:201], v[106:109]
	v_mfma_f32_16x16x32_bf16 v[102:105], v[166:169], v[198:201], v[102:105]
	v_mfma_f32_16x16x32_bf16 v[90:93], v[158:161], v[206:209], v[90:93]
	v_mfma_f32_16x16x32_bf16 v[86:89], v[166:169], v[206:209], v[86:89]
	v_mfma_f32_16x16x32_bf16 v[138:141], v[162:165], v[186:189], v[138:141]
	v_mfma_f32_16x16x32_bf16 v[134:137], v[170:173], v[186:189], v[134:137]
	v_mfma_f32_16x16x32_bf16 v[122:125], v[162:165], v[194:197], v[122:125]
	v_mfma_f32_16x16x32_bf16 v[118:121], v[170:173], v[194:197], v[118:121]
	v_mfma_f32_16x16x32_bf16 v[106:109], v[162:165], v[202:205], v[106:109]
	v_mfma_f32_16x16x32_bf16 v[102:105], v[170:173], v[202:205], v[102:105]
	v_mfma_f32_16x16x32_bf16 v[90:93], v[162:165], v[242:245], v[90:93]
	v_mfma_f32_16x16x32_bf16 v[86:89], v[170:173], v[242:245], v[86:89]
	v_mfma_f32_16x16x32_bf16 v[130:133], v[142:145], v[182:185], v[130:133]
	v_mfma_f32_16x16x32_bf16 v[126:129], v[150:153], v[182:185], v[126:129]
	v_mfma_f32_16x16x32_bf16 v[114:117], v[142:145], v[190:193], v[114:117]
	v_mfma_f32_16x16x32_bf16 v[110:113], v[150:153], v[190:193], v[110:113]
	v_mfma_f32_16x16x32_bf16 v[98:101], v[142:145], v[198:201], v[98:101]
	v_mfma_f32_16x16x32_bf16 v[94:97], v[150:153], v[198:201], v[94:97]
	v_mfma_f32_16x16x32_bf16 v[82:85], v[142:145], v[206:209], v[82:85]
	v_mfma_f32_16x16x32_bf16 v[78:81], v[150:153], v[206:209], v[78:81]
	v_mfma_f32_16x16x32_bf16 v[130:133], v[146:149], v[186:189], v[130:133]
	v_mfma_f32_16x16x32_bf16 v[126:129], v[154:157], v[186:189], v[126:129]
	v_mfma_f32_16x16x32_bf16 v[114:117], v[146:149], v[194:197], v[114:117]
	v_mfma_f32_16x16x32_bf16 v[110:113], v[154:157], v[194:197], v[110:113]
	v_mfma_f32_16x16x32_bf16 v[98:101], v[146:149], v[202:205], v[98:101]
	v_mfma_f32_16x16x32_bf16 v[94:97], v[154:157], v[202:205], v[94:97]
	v_mfma_f32_16x16x32_bf16 v[82:85], v[146:149], v[242:245], v[82:85]
	v_mfma_f32_16x16x32_bf16 v[78:81], v[154:157], v[242:245], v[78:81]
	s_and_b64 vcc, exec, s[6:7]
	s_cbranch_vccnz .LBB0_1373
	s_and_b64 vcc, exec, s[4:5]
	s_mov_b64 s[4:5], -1
	s_cbranch_vccnz .LBB0_1370
	v_mfma_f32_16x16x32_bf16 v[10:13], v[142:145], v[174:177], v[10:13]
	s_mov_b64 s[4:5], 0
	v_mfma_f32_16x16x32_bf16 v[6:9], v[150:153], v[174:177], v[6:9]
	v_mfma_f32_16x16x32_bf16 v[10:13], v[146:149], v[178:181], v[10:13]
	v_mfma_f32_16x16x32_bf16 v[6:9], v[154:157], v[178:181], v[6:9]

; #define PG8_STAGEX(b, gbase) do { if constexpr (XR) { if (lane < 16) __builtin_amdgcn_global_load_lds((const unsigned*)((const char*)(gbase) + voffX), (PG8_LAS unsigned*)(lds + XR_OFF + (b) * 2048 + wid * 256), 16, 0, 0); } } while (0)
; #define PG8_MMAX() do { if constexpr (XR) { if (hasx) { __builtin_amdgcn_s_setprio(1); if (wr == 0) PG8_MMAX_(B0); else PG8_MMAX_(B1); __builtin_amdgcn_s_setprio(0); } } } while (0)
; #define PG8_WAIT_LOOP() do { if constexpr (XR) PG8_WAIT_V(9); else PG8_WAIT_V(8); } while (0)
; #define PG8_STAGE(bufoff, gbase, voff) do { _Pragma("unroll") for (int _i = 0; _i < 2; ++_i) \
;         __builtin_amdgcn_global_load_lds((const unsigned*)((const char*)(gbase) + (voff)[_i]), (PG8_LAS unsigned*)(lds + (bufoff) + ldsw + _i * 8192), 16, 0, 0); } while (0)
; #define PG8_LDA(dst, b, h) do { _Pragma("unroll") for (int m = 0; m < 4; ++m) _Pragma("unroll") for (int k = 0; k < 2; ++k) dst[m][k] = *(const PG8_LAS bf16x8*)(lds + PG8_SA(b, h) + aoff + m * 2048 + k * 1024); } while (0)
; #define PG8_MMA(ai, bj, At, Bt) do { __builtin_amdgcn_s_setprio(1); _Pragma("unroll") for (int m = 0; m < 4; ++m) _Pragma("unroll") for (int n = 0; n < 2; ++n) _Pragma("unroll") for (int k = 0; k < 2; ++k) \
;         acc[ai][bj][m][n] = __builtin_amdgcn_mfma_f32_16x16x32_bf16(Bt[n][k], At[m][k], acc[ai][bj][m][n], 0, 0, 0); __builtin_amdgcn_s_setprio(0); } while (0)
; #define PG8_WAIT_L(n) asm volatile("s_waitcnt lgkmcnt(" #n ")" ::: "memory")
; #define PG8_BAR __builtin_amdgcn_s_barrier()
; #define PG8_SCHED __builtin_amdgcn_sched_barrier(0)
; template <class Epi, class Sched, bool ALIGN_EPI = false, bool SP2 = false, bool DRAIN = true, bool XR = false>
; __device__ __forceinline__ void gemm_phase(PG8_LAS unsigned char* lds, const Gemm g, const Sched& S, const Epi& E) {
;     ...
;             PG8_WAIT_LOOP(); PG8_WAIT_L(0); PG8_BAR; PG8_MMA(0, 0, At, B0); PG8_MMA(0, 1, At, B1); PG8_MMAX(); PG8_BAR; PG8_SCHED;
;             PG8_LDA(At, 1, 1); PG8_STAGE(PG8_SB(1, 0), b3, voffB); PG8_STAGE(PG8_SB(1, 1), b3 + hstep, voffB); PG8_STAGE(PG8_SA(1, 0), a3, voffA); PG8_STAGEX(1, x3);
.LBB0_1372:
.LBB0_1373:
	s_barrier
	s_mov_b32 m0, s23
	v_lshl_add_u64 v[206:207], v[224:225], 0, s[86:87]
	ds_read_b128 v[198:201], v249 offset:49152
	ds_read_b128 v[202:205], v249 offset:50176
	ds_read_b128 v[190:193], v249 offset:51200
	ds_read_b128 v[194:197], v249 offset:52224
	ds_read_b128 v[182:185], v249 offset:53248
	ds_read_b128 v[186:189], v249 offset:54272
	ds_read_b128 v[174:177], v249 offset:55296
	ds_read_b128 v[178:181], v249 offset:56320
	global_load_lds_dwordx4 v[206:207], off
	v_lshl_add_u64 v[206:207], v[226:227], 0, s[86:87]
	s_mov_b32 m0, s24
	s_nop 0
	global_load_lds_dwordx4 v[206:207], off
	v_lshl_add_u64 v[206:207], v[228:229], 0, s[86:87]
	s_mov_b32 m0, s27
	s_nop 0
	global_load_lds_dwordx4 v[206:207], off
	v_lshl_add_u64 v[206:207], v[230:231], 0, s[86:87]
	s_mov_b32 m0, s64
	s_nop 0
	global_load_lds_dwordx4 v[206:207], off
	v_lshl_add_u64 v[206:207], v[232:233], 0, s[86:87]
	s_mov_b32 m0, s25
	s_nop 0
	global_load_lds_dwordx4 v[206:207], off
	v_lshl_add_u64 v[206:207], v[234:235], 0, s[86:87]
	s_mov_b32 m0, s26
	s_nop 0
	global_load_lds_dwordx4 v[206:207], off
	s_and_saveexec_b64 s[4:5], s[0:1]
	s_cbranch_execz .LBB0_1375
	s_add_i32 s6, s12, 0
	v_lshl_add_u64 v[4:5], v[4:5], 0, s[86:87]
	s_add_i32 m0, s6, 0x22c00
	s_nop 0
	global_load_lds_dwordx4 v[4:5], off

; #define PG8_LDX(b) do { if constexpr (XR) { _Pragma("unroll") for (int k = 0; k < 2; ++k) Ax_[k] = *(const PG8_LAS bf16x8*)(lds + XR_OFF + (b) * 2048 + aoffx + k * 1024); } } while (0)
; #define PG8_MMAX() do { if constexpr (XR) { if (hasx) { __builtin_amdgcn_s_setprio(1); if (wr == 0) PG8_MMAX_(B0); else PG8_MMAX_(B1); __builtin_amdgcn_s_setprio(0); } } } while (0)
; #define PG8_WAIT_LOOP() do { if constexpr (XR) PG8_WAIT_V(9); else PG8_WAIT_V(8); } while (0)
; #define PG8_STAGE(bufoff, gbase, voff) do { _Pragma("unroll") for (int _i = 0; _i < 2; ++_i) \
;         __builtin_amdgcn_global_load_lds((const unsigned*)((const char*)(gbase) + (voff)[_i]), (PG8_LAS unsigned*)(lds + (bufoff) + ldsw + _i * 8192), 16, 0, 0); } while (0)
; #define PG8_LDA(dst, b, h) do { _Pragma("unroll") for (int m = 0; m < 4; ++m) _Pragma("unroll") for (int k = 0; k < 2; ++k) dst[m][k] = *(const PG8_LAS bf16x8*)(lds + PG8_SA(b, h) + aoff + m * 2048 + k * 1024); } while (0)
; #define PG8_LDB(dst, b, h) do { _Pragma("unroll") for (int n = 0; n < 2; ++n) _Pragma("unroll") for (int k = 0; k < 2; ++k) dst[n][k] = *(const PG8_LAS bf16x8*)(lds + PG8_SB(b, h) + boff + n * 2048 + k * 1024); } while (0)
; #define PG8_MMA(ai, bj, At, Bt) do { __builtin_amdgcn_s_setprio(1); _Pragma("unroll") for (int m = 0; m < 4; ++m) _Pragma("unroll") for (int n = 0; n < 2; ++n) _Pragma("unroll") for (int k = 0; k < 2; ++k) \
;         acc[ai][bj][m][n] = __builtin_amdgcn_mfma_f32_16x16x32_bf16(Bt[n][k], At[m][k], acc[ai][bj][m][n], 0, 0, 0); __builtin_amdgcn_s_setprio(0); } while (0)
; #define PG8_WAIT_L(n) asm volatile("s_waitcnt lgkmcnt(" #n ")" ::: "memory")
; #define PG8_BAR __builtin_amdgcn_s_barrier()
; #define PG8_SCHED __builtin_amdgcn_sched_barrier(0)
; template <class Epi, class Sched, bool ALIGN_EPI = false, bool SP2 = false, bool DRAIN = true, bool XR = false>
; __device__ __forceinline__ void gemm_phase(PG8_LAS unsigned char* lds, const Gemm g, const Sched& S, const Epi& E) {
;     ...
;             PG8_LDB(B0, 0, 0); PG8_LDB(B1, 0, 1); PG8_SCHED; PG8_LDA(At, 0, 0); PG8_LDX(0); PG8_STAGE(PG8_SA(1, 1), a1 + hstepA, voffA);
;             PG8_WAIT_LOOP(); PG8_WAIT_L(0); PG8_BAR; PG8_MMA(0, 0, At, B0); PG8_MMA(0, 1, At, B1); PG8_MMAX(); PG8_BAR; PG8_SCHED;
.LBB0_1501:
	s_add_i32 s64, s83, s70
	v_add_u32_e32 v140, 0x10000, v248
	v_add_u32_e32 v152, 0x14000, v248
	s_and_b32 s6, s64, s97
	ds_read_b128 v[156:159], v140
	ds_read_b128 v[160:163], v140 offset:1024
	ds_read_b128 v[164:167], v140 offset:2048
	ds_read_b128 v[168:171], v140 offset:3072
	ds_read_b128 v[140:143], v152
	ds_read_b128 v[144:147], v152 offset:1024
	ds_read_b128 v[148:151], v152 offset:2048
	ds_read_b128 v[152:155], v152 offset:3072
	s_lshr_b32 s84, s6, 2
	s_lshl_b32 s6, s6, 7
	s_lshl_b64 s[4:5], s[84:85], 9
	s_and_b32 s6, s6, 0x100
	s_add_u32 s4, s40, s4
	s_addc_u32 s5, s41, s5
	s_add_u32 s4, s4, s6
	s_addc_u32 s5, s5, 0
	s_add_u32 s4, s4, s28
	s_addc_u32 s5, s5, s29
	v_lshl_add_u64 v[212:213], s[4:5], 0, v[204:205]
	v_add_u32_e32 v176, 0x22400, v250
	v_lshl_add_u64 v[212:213], v[212:213], 0, s[86:87]
	s_add_i32 m0, s90, 0xc000
	ds_read_b128 v[180:183], v249
	ds_read_b128 v[184:187], v249 offset:1024
	ds_read_b128 v[188:191], v249 offset:2048
	ds_read_b128 v[192:195], v249 offset:3072
	ds_read_b128 v[196:199], v249 offset:4096
	ds_read_b128 v[200:203], v249 offset:5120
	ds_read_b128 v[206:209], v249 offset:6144
	ds_read_b128 v[222:225], v249 offset:7168
	ds_read_b128 v[172:175], v176
	ds_read_b128 v[176:179], v176 offset:1024
	global_load_lds_dwordx4 v[212:213], off
	v_lshl_add_u64 v[212:213], s[4:5], 0, v[216:217]
	v_lshl_add_u64 v[212:213], v[212:213], 0, s[86:87]
	s_add_i32 m0, s90, 0xe000
	s_nop 0
	global_load_lds_dwordx4 v[212:213], off
	s_waitcnt vmcnt(9)
	s_waitcnt lgkmcnt(0)
	s_barrier
	v_mfma_f32_16x16x32_bf16 v[136:139], v[156:159], v[180:183], v[136:139]
	v_mfma_f32_16x16x32_bf16 v[132:135], v[164:167], v[180:183], v[132:135]
	v_mfma_f32_16x16x32_bf16 v[128:131], v[156:159], v[188:191], v[128:131]
	v_mfma_f32_16x16x32_bf16 v[124:127], v[164:167], v[188:191], v[124:127]
	v_mfma_f32_16x16x32_bf16 v[120:123], v[156:159], v[196:199], v[120:123]
	v_mfma_f32_16x16x32_bf16 v[116:119], v[164:167], v[196:199], v[116:119]
	v_mfma_f32_16x16x32_bf16 v[112:115], v[156:159], v[206:209], v[112:115]
	v_mfma_f32_16x16x32_bf16 v[108:111], v[164:167], v[206:209], v[108:111]
	v_mfma_f32_16x16x32_bf16 v[136:139], v[160:163], v[184:187], v[136:139]
	v_mfma_f32_16x16x32_bf16 v[132:135], v[168:171], v[184:187], v[132:135]
	v_mfma_f32_16x16x32_bf16 v[128:131], v[160:163], v[192:195], v[128:131]
	v_mfma_f32_16x16x32_bf16 v[124:127], v[168:171], v[192:195], v[124:127]
	v_mfma_f32_16x16x32_bf16 v[120:123], v[160:163], v[200:203], v[120:123]
	v_mfma_f32_16x16x32_bf16 v[116:119], v[168:171], v[200:203], v[116:119]
	v_mfma_f32_16x16x32_bf16 v[112:115], v[160:163], v[222:225], v[112:115]
	v_mfma_f32_16x16x32_bf16 v[108:111], v[168:171], v[222:225], v[108:111]
	v_mfma_f32_16x16x32_bf16 v[104:107], v[140:143], v[180:183], v[104:107]
	v_mfma_f32_16x16x32_bf16 v[100:103], v[148:151], v[180:183], v[100:103]
	v_mfma_f32_16x16x32_bf16 v[96:99], v[140:143], v[188:191], v[96:99]
	v_mfma_f32_16x16x32_bf16 v[92:95], v[148:151], v[188:191], v[92:95]
	v_mfma_f32_16x16x32_bf16 v[88:91], v[140:143], v[196:199], v[88:91]
	v_mfma_f32_16x16x32_bf16 v[84:87], v[148:151], v[196:199], v[84:87]
	v_mfma_f32_16x16x32_bf16 v[80:83], v[140:143], v[206:209], v[80:83]
	v_mfma_f32_16x16x32_bf16 v[76:79], v[148:151], v[206:209], v[76:79]
	v_mfma_f32_16x16x32_bf16 v[104:107], v[144:147], v[184:187], v[104:107]
	v_mfma_f32_16x16x32_bf16 v[100:103], v[152:155], v[184:187], v[100:103]
	v_mfma_f32_16x16x32_bf16 v[96:99], v[144:147], v[192:195], v[96:99]
	v_mfma_f32_16x16x32_bf16 v[92:95], v[152:155], v[192:195], v[92:95]
	v_mfma_f32_16x16x32_bf16 v[88:91], v[144:147], v[200:203], v[88:91]
	v_mfma_f32_16x16x32_bf16 v[84:87], v[152:155], v[200:203], v[84:87]
	v_mfma_f32_16x16x32_bf16 v[80:83], v[144:147], v[222:225], v[80:83]
	v_mfma_f32_16x16x32_bf16 v[76:79], v[152:155], v[222:225], v[76:79]
	v_cndmask_b32_e64 v180, 0, 1, s[46:47]
	v_cmp_ne_u32_e64 s[6:7], 1, v180
	v_cndmask_b32_e64 v180, 0, 1, s[52:53]
	s_andn2_b64 vcc, exec, s[46:47]
	v_cmp_ne_u32_e64 s[4:5], 1, v180
	s_cbranch_vccnz .LBB0_1507
	s_and_b64 vcc, exec, s[4:5]
	s_mov_b64 s[62:63], -1
	s_cbranch_vccnz .LBB0_1504
	v_mfma_f32_16x16x32_bf16 v[8:11], v[140:143], v[172:175], v[8:11]
	s_mov_b64 s[62:63], 0
	v_mfma_f32_16x16x32_bf16 v[4:7], v[148:151], v[172:175], v[4:7]
	v_mfma_f32_16x16x32_bf16 v[8:11], v[144:147], v[176:179], v[8:11]
	v_mfma_f32_16x16x32_bf16 v[4:7], v[152:155], v[176:179], v[4:7]

; #define PG8_STAGEX(b, gbase) do { if constexpr (XR) { if (lane < 16) __builtin_amdgcn_global_load_lds((const unsigned*)((const char*)(gbase) + voffX), (PG8_LAS unsigned*)(lds + XR_OFF + (b) * 2048 + wid * 256), 16, 0, 0); } } while (0)
; #define PG8_LDX(b) do { if constexpr (XR) { _Pragma("unroll") for (int k = 0; k < 2; ++k) Ax_[k] = *(const PG8_LAS bf16x8*)(lds + XR_OFF + (b) * 2048 + aoffx + k * 1024); } } while (0)
; #define PG8_MMAX() do { if constexpr (XR) { if (hasx) { __builtin_amdgcn_s_setprio(1); if (wr == 0) PG8_MMAX_(B0); else PG8_MMAX_(B1); __builtin_amdgcn_s_setprio(0); } } } while (0)
; #define PG8_WAIT_LOOP() do { if constexpr (XR) PG8_WAIT_V(9); else PG8_WAIT_V(8); } while (0)
; #define PG8_STAGE(bufoff, gbase, voff) do { _Pragma("unroll") for (int _i = 0; _i < 2; ++_i) \
;         __builtin_amdgcn_global_load_lds((const unsigned*)((const char*)(gbase) + (voff)[_i]), (PG8_LAS unsigned*)(lds + (bufoff) + ldsw + _i * 8192), 16, 0, 0); } while (0)
; #define PG8_LDA(dst, b, h) do { _Pragma("unroll") for (int m = 0; m < 4; ++m) _Pragma("unroll") for (int k = 0; k < 2; ++k) dst[m][k] = *(const PG8_LAS bf16x8*)(lds + PG8_SA(b, h) + aoff + m * 2048 + k * 1024); } while (0)
; #define PG8_BAR __builtin_amdgcn_s_barrier()
; template <class Epi, class Sched, bool ALIGN_EPI = false, bool SP2 = false, bool DRAIN = true, bool XR = false>
; __device__ __forceinline__ void gemm_phase(PG8_LAS unsigned char* lds, const Gemm g, const Sched& S, const Epi& E) {
;     ...
;             const char* a1 = cA + PG8_KOA(t) + kstep;
;             const char* a2 = last ? nA + ka0 : cA + PG8_KOA(t + 2); const char* b2 = last ? nB + kb0 : cB + PG8_KOB(t + 2);
;             const char* x2 = XR ? (last ? nX + kx0 : cX + PG8_KOX(t + 2)) : nullptr; const char* x3 = XR ? x2 + kstep : nullptr;
;             const char* a3 = a2 + kstep; const char* b3 = b2 + kstep;
;             if (last && has_next) S.a_ready(nxt);
;             if constexpr (SP2) {
;             PG8_LDB(B0, 0, 0); PG8_LDB(B1, 0, 1); PG8_SCHED; PG8_LDA(At, 0, 0); PG8_LDX(0); PG8_STAGE(PG8_SA(1, 1), a1 + hstepA, voffA);
;             PG8_WAIT_LOOP(); PG8_WAIT_L(0); PG8_BAR; PG8_MMA(0, 0, At, B0); PG8_MMA(0, 1, At, B1); PG8_MMAX(); PG8_BAR; PG8_SCHED;
;             PG8_LDA(At, 0, 1); PG8_STAGE(PG8_SB(0, 0), b2, voffB); PG8_STAGE(PG8_SB(0, 1), b2 + hstep, voffB); PG8_STAGE(PG8_SA(0, 0), a2, voffA); PG8_STAGEX(0, x2);
.LBB0_1506:
.LBB0_1507:
	s_barrier
	s_add_i32 s64, s64, 2
	s_and_b32 s62, s64, s97
	s_lshr_b32 s84, s62, 2
	s_lshl_b32 s36, s62, 7
	s_lshl_b64 s[64:65], s[84:85], 9
	s_and_b32 s36, s36, 0x100
	s_add_u32 s63, s40, s64
	s_addc_u32 s64, s41, s65
	s_add_u32 s36, s63, s36
	s_mov_b32 s63, s85
	s_addc_u32 s64, s64, 0
	s_lshl_b64 s[62:63], s[62:63], 7
	s_add_u32 vcc_lo, s34, s62
	s_addc_u32 vcc_hi, s35, s63
	s_add_u32 s81, s42, s62
	s_addc_u32 s65, s43, s63
	s_cmp_eq_u32 s91, s70
	s_cselect_b32 s63, s8, s64
	s_cselect_b32 s62, s78, s36
	s_cselect_b32 s65, s69, s65
	s_cselect_b32 s64, s21, s81
	s_cselect_b32 vcc_hi, s20, vcc_hi
	s_cselect_b32 vcc_lo, s9, vcc_lo
	s_mov_b32 m0, s16
	v_lshl_add_u64 v[224:225], vcc, 0, v[214:215]
	v_lshl_add_u64 v[226:227], vcc, 0, v[218:219]
	s_add_u32 vcc_lo, vcc_lo, s28
	ds_read_b128 v[196:199], v249 offset:16384
	ds_read_b128 v[200:203], v249 offset:17408
	ds_read_b128 v[188:191], v249 offset:18432
	ds_read_b128 v[192:195], v249 offset:19456
	ds_read_b128 v[180:183], v249 offset:20480
	ds_read_b128 v[184:187], v249 offset:21504
	ds_read_b128 v[172:175], v249 offset:22528
	ds_read_b128 v[176:179], v249 offset:23552
	global_load_lds_dwordx4 v[224:225], off
	s_mov_b32 m0, s17
	s_addc_u32 vcc_hi, vcc_hi, s29
	global_load_lds_dwordx4 v[226:227], off
	v_lshl_add_u64 v[228:229], vcc, 0, v[214:215]
	s_mov_b32 m0, s93
	v_lshl_add_u64 v[230:231], vcc, 0, v[218:219]
	global_load_lds_dwordx4 v214, vcc
	s_mov_b32 m0, s24
	v_lshl_add_u64 v[232:233], s[62:63], 0, v[204:205]
	global_load_lds_dwordx4 v218, vcc
	s_mov_b32 m0, s90
	v_lshl_add_u64 v[234:235], s[62:63], 0, v[216:217]
	global_load_lds_dwordx4 v204, s[62:63]
	s_mov_b32 m0, s25
	v_lshl_add_u64 v[222:223], s[64:65], 0, v[220:221]
	global_load_lds_dwordx4 v216, s[62:63]
	s_and_saveexec_b64 s[64:65], s[2:3]
	s_cbranch_execz .LBB0_1509
	s_add_i32 s36, s26, 0
	s_add_i32 m0, s36, 0x22400
	s_nop 0
	global_load_lds_dwordx4 v[222:223], off
; #define PG8_LDX(b) do { if constexpr (XR) { _Pragma("unroll") for (int k = 0; k < 2; ++k) Ax_[k] = *(const PG8_LAS bf16x8*)(lds + XR_OFF + (b) * 2048 + aoffx + k * 1024); } } while (0)
; #define PG8_MMAX() do { if constexpr (XR) { if (hasx) { __builtin_amdgcn_s_setprio(1); if (wr == 0) PG8_MMAX_(B0); else PG8_MMAX_(B1); __builtin_amdgcn_s_setprio(0); } } } while (0)
; #define PG8_WAIT_LOOP() do { if constexpr (XR) PG8_WAIT_V(9); else PG8_WAIT_V(8); } while (0)
; #define PG8_STAGE(bufoff, gbase, voff) do { _Pragma("unroll") for (int _i = 0; _i < 2; ++_i) \
;         __builtin_amdgcn_global_load_lds((const unsigned*)((const char*)(gbase) + (voff)[_i]), (PG8_LAS unsigned*)(lds + (bufoff) + ldsw + _i * 8192), 16, 0, 0); } while (0)
; #define PG8_LDA(dst, b, h) do { _Pragma("unroll") for (int m = 0; m < 4; ++m) _Pragma("unroll") for (int k = 0; k < 2; ++k) dst[m][k] = *(const PG8_LAS bf16x8*)(lds + PG8_SA(b, h) + aoff + m * 2048 + k * 1024); } while (0)
; #define PG8_LDB(dst, b, h) do { _Pragma("unroll") for (int n = 0; n < 2; ++n) _Pragma("unroll") for (int k = 0; k < 2; ++k) dst[n][k] = *(const PG8_LAS bf16x8*)(lds + PG8_SB(b, h) + boff + n * 2048 + k * 1024); } while (0)
; #define PG8_MMA(ai, bj, At, Bt) do { __builtin_amdgcn_s_setprio(1); _Pragma("unroll") for (int m = 0; m < 4; ++m) _Pragma("unroll") for (int n = 0; n < 2; ++n) _Pragma("unroll") for (int k = 0; k < 2; ++k) \
;         acc[ai][bj][m][n] = __builtin_amdgcn_mfma_f32_16x16x32_bf16(Bt[n][k], At[m][k], acc[ai][bj][m][n], 0, 0, 0); __builtin_amdgcn_s_setprio(0); } while (0)
; #define PG8_WAIT_L(n) asm volatile("s_waitcnt lgkmcnt(" #n ")" ::: "memory")
; #define PG8_BAR __builtin_amdgcn_s_barrier()
; #define PG8_SCHED __builtin_amdgcn_sched_barrier(0)
; template <class Epi, class Sched, bool ALIGN_EPI = false, bool SP2 = false, bool DRAIN = true, bool XR = false>
; __device__ __forceinline__ void gemm_phase(PG8_LAS unsigned char* lds, const Gemm g, const Sched& S, const Epi& E) {
;     ...
;             PG8_WAIT_LOOP(); PG8_WAIT_L(0); PG8_BAR; PG8_MMA(1, 0, At, B0); PG8_MMA(1, 1, At, B1); PG8_BAR; PG8_SCHED;
;             PG8_LDB(B0, 1, 0); PG8_LDB(B1, 1, 1); PG8_SCHED; PG8_LDA(At, 1, 0); PG8_LDX(1); PG8_STAGE(PG8_SA(0, 1), a2 + hstepA, voffA);
;             PG8_WAIT_LOOP(); PG8_WAIT_L(0); PG8_BAR; PG8_MMA(0, 0, At, B0); PG8_MMA(0, 1, At, B1); PG8_MMAX(); PG8_BAR; PG8_SCHED;
.LBB0_1509:
	s_or_b64 exec, exec, s[64:65]
	s_waitcnt vmcnt(9)
	s_waitcnt lgkmcnt(0)
	s_barrier
	v_mfma_f32_16x16x32_bf16 v[72:75], v[156:159], v[196:199], v[72:75]
	v_mfma_f32_16x16x32_bf16 v[68:71], v[164:167], v[196:199], v[68:71]
	v_mfma_f32_16x16x32_bf16 v[64:67], v[156:159], v[188:191], v[64:67]
	v_mfma_f32_16x16x32_bf16 v[60:63], v[164:167], v[188:191], v[60:63]
	v_mfma_f32_16x16x32_bf16 v[56:59], v[156:159], v[180:183], v[56:59]
	v_mfma_f32_16x16x32_bf16 v[52:55], v[164:167], v[180:183], v[52:55]
	v_mfma_f32_16x16x32_bf16 v[48:51], v[156:159], v[172:175], v[48:51]
	v_mfma_f32_16x16x32_bf16 v[44:47], v[164:167], v[172:175], v[44:47]
	v_mfma_f32_16x16x32_bf16 v[72:75], v[160:163], v[200:203], v[72:75]
	v_mfma_f32_16x16x32_bf16 v[68:71], v[168:171], v[200:203], v[68:71]
	v_mfma_f32_16x16x32_bf16 v[64:67], v[160:163], v[192:195], v[64:67]
	v_mfma_f32_16x16x32_bf16 v[60:63], v[168:171], v[192:195], v[60:63]
	v_mfma_f32_16x16x32_bf16 v[56:59], v[160:163], v[184:187], v[56:59]
	v_mfma_f32_16x16x32_bf16 v[52:55], v[168:171], v[184:187], v[52:55]
	v_mfma_f32_16x16x32_bf16 v[48:51], v[160:163], v[176:179], v[48:51]
	v_mfma_f32_16x16x32_bf16 v[44:47], v[168:171], v[176:179], v[44:47]
	v_mfma_f32_16x16x32_bf16 v[40:43], v[140:143], v[196:199], v[40:43]
	v_mfma_f32_16x16x32_bf16 v[36:39], v[148:151], v[196:199], v[36:39]
	v_mfma_f32_16x16x32_bf16 v[32:35], v[140:143], v[188:191], v[32:35]
	v_mfma_f32_16x16x32_bf16 v[28:31], v[148:151], v[188:191], v[28:31]
	v_mfma_f32_16x16x32_bf16 v[24:27], v[140:143], v[180:183], v[24:27]
	v_mfma_f32_16x16x32_bf16 v[20:23], v[148:151], v[180:183], v[20:23]
	v_mfma_f32_16x16x32_bf16 v[16:19], v[140:143], v[172:175], v[16:19]
	v_mfma_f32_16x16x32_bf16 v[12:15], v[148:151], v[172:175], v[12:15]
	v_mfma_f32_16x16x32_bf16 v[40:43], v[144:147], v[200:203], v[40:43]
	v_mfma_f32_16x16x32_bf16 v[36:39], v[152:155], v[200:203], v[36:39]
	v_mfma_f32_16x16x32_bf16 v[32:35], v[144:147], v[192:195], v[32:35]
	v_mfma_f32_16x16x32_bf16 v[28:31], v[152:155], v[192:195], v[28:31]
	v_mfma_f32_16x16x32_bf16 v[24:27], v[144:147], v[184:187], v[24:27]
	v_mfma_f32_16x16x32_bf16 v[20:23], v[152:155], v[184:187], v[20:23]
	v_mfma_f32_16x16x32_bf16 v[16:19], v[144:147], v[176:179], v[16:19]
	v_mfma_f32_16x16x32_bf16 v[12:15], v[152:155], v[176:179], v[12:15]
	s_barrier
	v_add_u32_e32 v140, 0x18000, v248
	v_add_u32_e32 v152, 0x1c000, v248
	ds_read_b128 v[156:159], v140
	ds_read_b128 v[160:163], v140 offset:1024
	ds_read_b128 v[164:167], v140 offset:2048
	ds_read_b128 v[168:171], v140 offset:3072
	ds_read_b128 v[140:143], v152
	ds_read_b128 v[144:147], v152 offset:1024
	ds_read_b128 v[148:151], v152 offset:2048
	ds_read_b128 v[152:155], v152 offset:3072
	s_add_u32 s62, s62, s28
	s_addc_u32 s63, s63, s29
	s_mov_b32 m0, s12
	v_add_u32_e32 v176, 0x22c00, v250
	ds_read_b128 v[180:183], v249 offset:32768
	ds_read_b128 v[184:187], v249 offset:33792
	ds_read_b128 v[188:191], v249 offset:34816
	ds_read_b128 v[192:195], v249 offset:35840
	ds_read_b128 v[196:199], v249 offset:36864
	ds_read_b128 v[200:203], v249 offset:37888
	ds_read_b128 v[206:209], v249 offset:38912
	ds_read_b128 v[242:245], v249 offset:39936
	ds_read_b128 v[172:175], v176
	ds_read_b128 v[176:179], v176 offset:1024
	global_load_lds_dwordx4 v204, s[62:63]
	s_mov_b32 m0, s13
	s_nop 0
	global_load_lds_dwordx4 v216, s[62:63]
	s_waitcnt vmcnt(9)
	s_waitcnt lgkmcnt(0)
	s_barrier
	v_mfma_f32_16x16x32_bf16 v[136:139], v[156:159], v[180:183], v[136:139]
	v_mfma_f32_16x16x32_bf16 v[132:135], v[164:167], v[180:183], v[132:135]
	v_mfma_f32_16x16x32_bf16 v[128:131], v[156:159], v[188:191], v[128:131]
	v_mfma_f32_16x16x32_bf16 v[124:127], v[164:167], v[188:191], v[124:127]
	v_mfma_f32_16x16x32_bf16 v[120:123], v[156:159], v[196:199], v[120:123]
	v_mfma_f32_16x16x32_bf16 v[116:119], v[164:167], v[196:199], v[116:119]
	v_mfma_f32_16x16x32_bf16 v[112:115], v[156:159], v[206:209], v[112:115]
	v_mfma_f32_16x16x32_bf16 v[108:111], v[164:167], v[206:209], v[108:111]
	v_mfma_f32_16x16x32_bf16 v[136:139], v[160:163], v[184:187], v[136:139]
	v_mfma_f32_16x16x32_bf16 v[132:135], v[168:171], v[184:187], v[132:135]
	v_mfma_f32_16x16x32_bf16 v[128:131], v[160:163], v[192:195], v[128:131]
	v_mfma_f32_16x16x32_bf16 v[124:127], v[168:171], v[192:195], v[124:127]
	v_mfma_f32_16x16x32_bf16 v[120:123], v[160:163], v[200:203], v[120:123]
	v_mfma_f32_16x16x32_bf16 v[116:119], v[168:171], v[200:203], v[116:119]
	v_mfma_f32_16x16x32_bf16 v[112:115], v[160:163], v[242:245], v[112:115]
	v_mfma_f32_16x16x32_bf16 v[108:111], v[168:171], v[242:245], v[108:111]
	v_mfma_f32_16x16x32_bf16 v[104:107], v[140:143], v[180:183], v[104:107]
	v_mfma_f32_16x16x32_bf16 v[100:103], v[148:151], v[180:183], v[100:103]
	v_mfma_f32_16x16x32_bf16 v[96:99], v[140:143], v[188:191], v[96:99]
	v_mfma_f32_16x16x32_bf16 v[92:95], v[148:151], v[188:191], v[92:95]
	v_mfma_f32_16x16x32_bf16 v[88:91], v[140:143], v[196:199], v[88:91]
	v_mfma_f32_16x16x32_bf16 v[84:87], v[148:151], v[196:199], v[84:87]
	v_mfma_f32_16x16x32_bf16 v[80:83], v[140:143], v[206:209], v[80:83]
	v_mfma_f32_16x16x32_bf16 v[76:79], v[148:151], v[206:209], v[76:79]
	v_mfma_f32_16x16x32_bf16 v[104:107], v[144:147], v[184:187], v[104:107]
	v_mfma_f32_16x16x32_bf16 v[100:103], v[152:155], v[184:187], v[100:103]
	v_mfma_f32_16x16x32_bf16 v[96:99], v[144:147], v[192:195], v[96:99]
	v_mfma_f32_16x16x32_bf16 v[92:95], v[152:155], v[192:195], v[92:95]
	v_mfma_f32_16x16x32_bf16 v[88:91], v[144:147], v[200:203], v[88:91]
	v_mfma_f32_16x16x32_bf16 v[84:87], v[152:155], v[200:203], v[84:87]
	v_mfma_f32_16x16x32_bf16 v[80:83], v[144:147], v[242:245], v[80:83]
	v_mfma_f32_16x16x32_bf16 v[76:79], v[152:155], v[242:245], v[76:79]
	s_and_b64 vcc, exec, s[6:7]
	s_cbranch_vccnz .LBB0_1515
	s_and_b64 vcc, exec, s[4:5]
	s_mov_b64 s[4:5], -1
	s_cbranch_vccnz .LBB0_1512
	v_mfma_f32_16x16x32_bf16 v[8:11], v[140:143], v[172:175], v[8:11]
	s_mov_b64 s[4:5], 0
	v_mfma_f32_16x16x32_bf16 v[4:7], v[148:151], v[172:175], v[4:7]
	v_mfma_f32_16x16x32_bf16 v[8:11], v[144:147], v[176:179], v[8:11]
	v_mfma_f32_16x16x32_bf16 v[4:7], v[152:155], v[176:179], v[4:7]

; #define PG8_STAGEX(b, gbase) do { if constexpr (XR) { if (lane < 16) __builtin_amdgcn_global_load_lds((const unsigned*)((const char*)(gbase) + voffX), (PG8_LAS unsigned*)(lds + XR_OFF + (b) * 2048 + wid * 256), 16, 0, 0); } } while (0)
; #define PG8_MMAX() do { if constexpr (XR) { if (hasx) { __builtin_amdgcn_s_setprio(1); if (wr == 0) PG8_MMAX_(B0); else PG8_MMAX_(B1); __builtin_amdgcn_s_setprio(0); } } } while (0)
; #define PG8_WAIT_LOOP() do { if constexpr (XR) PG8_WAIT_V(9); else PG8_WAIT_V(8); } while (0)
; #define PG8_STAGE(bufoff, gbase, voff) do { _Pragma("unroll") for (int _i = 0; _i < 2; ++_i) \
;         __builtin_amdgcn_global_load_lds((const unsigned*)((const char*)(gbase) + (voff)[_i]), (PG8_LAS unsigned*)(lds + (bufoff) + ldsw + _i * 8192), 16, 0, 0); } while (0)
; #define PG8_LDA(dst, b, h) do { _Pragma("unroll") for (int m = 0; m < 4; ++m) _Pragma("unroll") for (int k = 0; k < 2; ++k) dst[m][k] = *(const PG8_LAS bf16x8*)(lds + PG8_SA(b, h) + aoff + m * 2048 + k * 1024); } while (0)
; #define PG8_MMA(ai, bj, At, Bt) do { __builtin_amdgcn_s_setprio(1); _Pragma("unroll") for (int m = 0; m < 4; ++m) _Pragma("unroll") for (int n = 0; n < 2; ++n) _Pragma("unroll") for (int k = 0; k < 2; ++k) \
;         acc[ai][bj][m][n] = __builtin_amdgcn_mfma_f32_16x16x32_bf16(Bt[n][k], At[m][k], acc[ai][bj][m][n], 0, 0, 0); __builtin_amdgcn_s_setprio(0); } while (0)
; #define PG8_WAIT_L(n) asm volatile("s_waitcnt lgkmcnt(" #n ")" ::: "memory")
; #define PG8_BAR __builtin_amdgcn_s_barrier()
; #define PG8_SCHED __builtin_amdgcn_sched_barrier(0)
; template <class Epi, class Sched, bool ALIGN_EPI = false, bool SP2 = false, bool DRAIN = true, bool XR = false>
; __device__ __forceinline__ void gemm_phase(PG8_LAS unsigned char* lds, const Gemm g, const Sched& S, const Epi& E) {
;     ...
;             PG8_WAIT_LOOP(); PG8_WAIT_L(0); PG8_BAR; PG8_MMA(0, 0, At, B0); PG8_MMA(0, 1, At, B1); PG8_MMAX(); PG8_BAR; PG8_SCHED;
;             PG8_LDA(At, 1, 1); PG8_STAGE(PG8_SB(1, 0), b3, voffB); PG8_STAGE(PG8_SB(1, 1), b3 + hstep, voffB); PG8_STAGE(PG8_SA(1, 0), a3, voffA); PG8_STAGEX(1, x3);
.LBB0_1514:
.LBB0_1515:
	s_barrier
	s_mov_b32 m0, s18
	v_lshl_add_u64 v[206:207], v[224:225], 0, s[86:87]
	ds_read_b128 v[196:199], v249 offset:49152
	ds_read_b128 v[200:203], v249 offset:50176
	ds_read_b128 v[188:191], v249 offset:51200
	ds_read_b128 v[192:195], v249 offset:52224
	ds_read_b128 v[180:183], v249 offset:53248
	ds_read_b128 v[184:187], v249 offset:54272
	ds_read_b128 v[172:175], v249 offset:55296
	ds_read_b128 v[176:179], v249 offset:56320
	global_load_lds_dwordx4 v[206:207], off
	v_lshl_add_u64 v[206:207], v[226:227], 0, s[86:87]
	s_mov_b32 m0, s19
	s_nop 0
	global_load_lds_dwordx4 v[206:207], off
	v_lshl_add_u64 v[206:207], v[228:229], 0, s[86:87]
	s_mov_b32 m0, s89
	s_nop 0
	global_load_lds_dwordx4 v[206:207], off
	v_lshl_add_u64 v[206:207], v[230:231], 0, s[86:87]
	s_mov_b32 m0, s88
	s_nop 0
	global_load_lds_dwordx4 v[206:207], off
	v_lshl_add_u64 v[206:207], v[232:233], 0, s[86:87]
	s_mov_b32 m0, s22
	s_nop 0
	global_load_lds_dwordx4 v[206:207], off
	v_lshl_add_u64 v[206:207], v[234:235], 0, s[86:87]
	s_mov_b32 m0, s23
	s_nop 0
	global_load_lds_dwordx4 v[206:207], off
	s_and_saveexec_b64 s[4:5], s[2:3]
	s_cbranch_execz .LBB0_1500
	s_add_i32 s6, s26, 0
	v_lshl_add_u64 v[206:207], v[222:223], 0, s[86:87]
	s_add_i32 m0, s6, 0x22c00
	s_nop 0
	global_load_lds_dwordx4 v[206:207], off
	s_branch .LBB0_1500

; #define PG8_LDX(b) do { if constexpr (XR) { _Pragma("unroll") for (int k = 0; k < 2; ++k) Ax_[k] = *(const PG8_LAS bf16x8*)(lds + XR_OFF + (b) * 2048 + aoffx + k * 1024); } } while (0)
; #define PG8_MMAX() do { if constexpr (XR) { if (hasx) { __builtin_amdgcn_s_setprio(1); if (wr == 0) PG8_MMAX_(B0); else PG8_MMAX_(B1); __builtin_amdgcn_s_setprio(0); } } } while (0)
; #define PG8_WAIT_LOOP() do { if constexpr (XR) PG8_WAIT_V(9); else PG8_WAIT_V(8); } while (0)
; #define PG8_STAGE(bufoff, gbase, voff) do { _Pragma("unroll") for (int _i = 0; _i < 2; ++_i) \
;         __builtin_amdgcn_global_load_lds((const unsigned*)((const char*)(gbase) + (voff)[_i]), (PG8_LAS unsigned*)(lds + (bufoff) + ldsw + _i * 8192), 16, 0, 0); } while (0)
; #define PG8_LDA(dst, b, h) do { _Pragma("unroll") for (int m = 0; m < 4; ++m) _Pragma("unroll") for (int k = 0; k < 2; ++k) dst[m][k] = *(const PG8_LAS bf16x8*)(lds + PG8_SA(b, h) + aoff + m * 2048 + k * 1024); } while (0)
; #define PG8_LDB(dst, b, h) do { _Pragma("unroll") for (int n = 0; n < 2; ++n) _Pragma("unroll") for (int k = 0; k < 2; ++k) dst[n][k] = *(const PG8_LAS bf16x8*)(lds + PG8_SB(b, h) + boff + n * 2048 + k * 1024); } while (0)
; #define PG8_MMA(ai, bj, At, Bt) do { __builtin_amdgcn_s_setprio(1); _Pragma("unroll") for (int m = 0; m < 4; ++m) _Pragma("unroll") for (int n = 0; n < 2; ++n) _Pragma("unroll") for (int k = 0; k < 2; ++k) \
;         acc[ai][bj][m][n] = __builtin_amdgcn_mfma_f32_16x16x32_bf16(Bt[n][k], At[m][k], acc[ai][bj][m][n], 0, 0, 0); __builtin_amdgcn_s_setprio(0); } while (0)
; #define PG8_WAIT_L(n) asm volatile("s_waitcnt lgkmcnt(" #n ")" ::: "memory")
; #define PG8_BAR __builtin_amdgcn_s_barrier()
; #define PG8_SCHED __builtin_amdgcn_sched_barrier(0)
; template <class Epi, class Sched, bool ALIGN_EPI = false, bool SP2 = false, bool DRAIN = true, bool XR = false>
; __device__ __forceinline__ void gemm_phase(PG8_LAS unsigned char* lds, const Gemm g, const Sched& S, const Epi& E) {
;     ...
;             PG8_LDB(B0, 0, 0); PG8_LDB(B1, 0, 1); PG8_SCHED; PG8_LDA(At, 0, 0); PG8_LDX(0); PG8_STAGE(PG8_SA(1, 1), a1 + hstepA, voffA);
;             PG8_WAIT_LOOP(); PG8_WAIT_L(0); PG8_BAR; PG8_MMA(0, 0, At, B0); PG8_MMA(0, 1, At, B1); PG8_MMAX(); PG8_BAR; PG8_SCHED;
.LBB0_1652:
	v_add_u32_e32 v2, 0x10000, v248
	s_add_i32 s46, s54, s89
	ds_read_b128 v[158:161], v2
	ds_read_b128 v[162:165], v2 offset:1024
	ds_read_b128 v[166:169], v2 offset:2048
	ds_read_b128 v[170:173], v2 offset:3072
	v_add_u32_e32 v2, 0x14000, v248
	s_and_b32 s6, s46, s59
	ds_read_b128 v[142:145], v2
	ds_read_b128 v[146:149], v2 offset:1024
	ds_read_b128 v[150:153], v2 offset:2048
	ds_read_b128 v[154:157], v2 offset:3072
	s_lshr_b32 s84, s6, 2
	s_lshl_b32 s6, s6, 7
	s_lshl_b64 s[0:1], s[84:85], 17
	s_and_b32 s6, s6, 0x100
	s_add_u32 s0, s40, s0
	s_addc_u32 s1, s41, s1
	s_add_u32 s0, s0, s6
	s_addc_u32 s1, s1, 0
	s_add_u32 s0, s0, 0x10080
	s_addc_u32 s1, s1, 0
	v_add_u32_e32 v2, 0x22400, v250
	s_add_i32 m0, s63, 0xc000
	ds_read_b128 v[182:185], v249
	ds_read_b128 v[186:189], v249 offset:1024
	ds_read_b128 v[190:193], v249 offset:2048
	ds_read_b128 v[194:197], v249 offset:3072
	ds_read_b128 v[198:201], v249 offset:4096
	ds_read_b128 v[202:205], v249 offset:5120
	ds_read_b128 v[206:209], v249 offset:6144
	ds_read_b128 v[224:227], v249 offset:7168
	ds_read_b128 v[174:177], v2
	ds_read_b128 v[178:181], v2 offset:1024
	global_load_lds_dwordx4 v214, s[0:1]
	s_add_i32 m0, s63, 0xe000
	s_nop 0
	global_load_lds_dwordx4 v218, s[0:1]
	s_waitcnt vmcnt(9)
	s_waitcnt lgkmcnt(0)
	s_barrier
	v_mfma_f32_16x16x32_bf16 v[138:141], v[158:161], v[182:185], v[138:141]
	v_mfma_f32_16x16x32_bf16 v[134:137], v[166:169], v[182:185], v[134:137]
	v_mfma_f32_16x16x32_bf16 v[122:125], v[158:161], v[190:193], v[122:125]
	v_mfma_f32_16x16x32_bf16 v[118:121], v[166:169], v[190:193], v[118:121]
	v_mfma_f32_16x16x32_bf16 v[106:109], v[158:161], v[198:201], v[106:109]
	v_mfma_f32_16x16x32_bf16 v[102:105], v[166:169], v[198:201], v[102:105]
	v_mfma_f32_16x16x32_bf16 v[90:93], v[158:161], v[206:209], v[90:93]
	v_mfma_f32_16x16x32_bf16 v[86:89], v[166:169], v[206:209], v[86:89]
	v_mfma_f32_16x16x32_bf16 v[138:141], v[162:165], v[186:189], v[138:141]
	v_mfma_f32_16x16x32_bf16 v[134:137], v[170:173], v[186:189], v[134:137]
	v_mfma_f32_16x16x32_bf16 v[122:125], v[162:165], v[194:197], v[122:125]
	v_mfma_f32_16x16x32_bf16 v[118:121], v[170:173], v[194:197], v[118:121]
	v_mfma_f32_16x16x32_bf16 v[106:109], v[162:165], v[202:205], v[106:109]
	v_mfma_f32_16x16x32_bf16 v[102:105], v[170:173], v[202:205], v[102:105]
	v_mfma_f32_16x16x32_bf16 v[90:93], v[162:165], v[224:227], v[90:93]
	v_mfma_f32_16x16x32_bf16 v[86:89], v[170:173], v[224:227], v[86:89]
	v_mfma_f32_16x16x32_bf16 v[130:133], v[142:145], v[182:185], v[130:133]
	v_mfma_f32_16x16x32_bf16 v[126:129], v[150:153], v[182:185], v[126:129]
	v_mfma_f32_16x16x32_bf16 v[114:117], v[142:145], v[190:193], v[114:117]
	v_mfma_f32_16x16x32_bf16 v[110:113], v[150:153], v[190:193], v[110:113]
	v_mfma_f32_16x16x32_bf16 v[98:101], v[142:145], v[198:201], v[98:101]
	v_mfma_f32_16x16x32_bf16 v[94:97], v[150:153], v[198:201], v[94:97]
	v_mfma_f32_16x16x32_bf16 v[82:85], v[142:145], v[206:209], v[82:85]
	v_mfma_f32_16x16x32_bf16 v[78:81], v[150:153], v[206:209], v[78:81]
	v_mfma_f32_16x16x32_bf16 v[130:133], v[146:149], v[186:189], v[130:133]
	v_mfma_f32_16x16x32_bf16 v[126:129], v[154:157], v[186:189], v[126:129]
	v_mfma_f32_16x16x32_bf16 v[114:117], v[146:149], v[194:197], v[114:117]
	v_mfma_f32_16x16x32_bf16 v[110:113], v[154:157], v[194:197], v[110:113]
	v_mfma_f32_16x16x32_bf16 v[98:101], v[146:149], v[202:205], v[98:101]
	v_mfma_f32_16x16x32_bf16 v[94:97], v[154:157], v[202:205], v[94:97]
	v_mfma_f32_16x16x32_bf16 v[82:85], v[146:149], v[224:227], v[82:85]
	v_mfma_f32_16x16x32_bf16 v[78:81], v[154:157], v[224:227], v[78:81]
	v_cndmask_b32_e64 v2, 0, 1, s[30:31]
	v_cmp_ne_u32_e64 s[6:7], 1, v2
	v_cndmask_b32_e64 v2, 0, 1, s[22:23]
	s_andn2_b64 vcc, exec, s[30:31]
	v_cmp_ne_u32_e64 s[0:1], 1, v2
	s_cbranch_vccnz .LBB0_1658
	s_and_b64 vcc, exec, s[0:1]
	s_mov_b64 s[44:45], -1
	s_cbranch_vccnz .LBB0_1655
	v_mfma_f32_16x16x32_bf16 v[10:13], v[142:145], v[174:177], v[10:13]
	s_mov_b64 s[44:45], 0
	v_mfma_f32_16x16x32_bf16 v[6:9], v[150:153], v[174:177], v[6:9]
	v_mfma_f32_16x16x32_bf16 v[10:13], v[146:149], v[178:181], v[10:13]
	v_mfma_f32_16x16x32_bf16 v[6:9], v[154:157], v[178:181], v[6:9]

; #define PG8_STAGEX(b, gbase) do { if constexpr (XR) { if (lane < 16) __builtin_amdgcn_global_load_lds((const unsigned*)((const char*)(gbase) + voffX), (PG8_LAS unsigned*)(lds + XR_OFF + (b) * 2048 + wid * 256), 16, 0, 0); } } while (0)
; #define PG8_LDX(b) do { if constexpr (XR) { _Pragma("unroll") for (int k = 0; k < 2; ++k) Ax_[k] = *(const PG8_LAS bf16x8*)(lds + XR_OFF + (b) * 2048 + aoffx + k * 1024); } } while (0)
; #define PG8_MMAX() do { if constexpr (XR) { if (hasx) { __builtin_amdgcn_s_setprio(1); if (wr == 0) PG8_MMAX_(B0); else PG8_MMAX_(B1); __builtin_amdgcn_s_setprio(0); } } } while (0)
; #define PG8_WAIT_LOOP() do { if constexpr (XR) PG8_WAIT_V(9); else PG8_WAIT_V(8); } while (0)
; #define PG8_STAGE(bufoff, gbase, voff) do { _Pragma("unroll") for (int _i = 0; _i < 2; ++_i) \
;         __builtin_amdgcn_global_load_lds((const unsigned*)((const char*)(gbase) + (voff)[_i]), (PG8_LAS unsigned*)(lds + (bufoff) + ldsw + _i * 8192), 16, 0, 0); } while (0)
; #define PG8_LDA(dst, b, h) do { _Pragma("unroll") for (int m = 0; m < 4; ++m) _Pragma("unroll") for (int k = 0; k < 2; ++k) dst[m][k] = *(const PG8_LAS bf16x8*)(lds + PG8_SA(b, h) + aoff + m * 2048 + k * 1024); } while (0)
; #define PG8_BAR __builtin_amdgcn_s_barrier()
; template <class Epi, class Sched, bool ALIGN_EPI = false, bool SP2 = false, bool DRAIN = true, bool XR = false>
; __device__ __forceinline__ void gemm_phase(PG8_LAS unsigned char* lds, const Gemm g, const Sched& S, const Epi& E) {
;     ...
;             const char* a1 = cA + PG8_KOA(t) + kstep;
;             const char* a2 = last ? nA + ka0 : cA + PG8_KOA(t + 2); const char* b2 = last ? nB + kb0 : cB + PG8_KOB(t + 2);
;             const char* x2 = XR ? (last ? nX + kx0 : cX + PG8_KOX(t + 2)) : nullptr; const char* x3 = XR ? x2 + kstep : nullptr;
;             const char* a3 = a2 + kstep; const char* b3 = b2 + kstep;
;             if (last && has_next) S.a_ready(nxt);
;             if constexpr (SP2) {
;             PG8_LDB(B0, 0, 0); PG8_LDB(B1, 0, 1); PG8_SCHED; PG8_LDA(At, 0, 0); PG8_LDX(0); PG8_STAGE(PG8_SA(1, 1), a1 + hstepA, voffA);
;             PG8_WAIT_LOOP(); PG8_WAIT_L(0); PG8_BAR; PG8_MMA(0, 0, At, B0); PG8_MMA(0, 1, At, B1); PG8_MMAX(); PG8_BAR; PG8_SCHED;
;             PG8_LDA(At, 0, 1); PG8_STAGE(PG8_SB(0, 0), b2, voffB); PG8_STAGE(PG8_SB(0, 1), b2 + hstep, voffB); PG8_STAGE(PG8_SA(0, 0), a2, voffA); PG8_STAGEX(0, x2);
.LBB0_1657:
.LBB0_1658:
	s_barrier
	s_add_i32 s46, s46, 2
	s_and_b32 s44, s46, s59
	s_lshr_b32 s84, s44, 2
	s_lshl_b32 s36, s44, 7
	s_lshl_b64 s[46:47], s[84:85], 17
	s_and_b32 s36, s36, 0x100
	s_add_u32 s45, s40, s46
	s_addc_u32 s46, s41, s47
	s_add_u32 s36, s45, s36
	s_mov_b32 s45, s85
	s_addc_u32 s46, s46, 0
	s_lshl_b64 s[44:45], s[44:45], 7
	s_add_u32 vcc_lo, s34, s44
	s_addc_u32 vcc_hi, s35, s45
	s_add_u32 s12, s42, s44
	s_addc_u32 s13, s43, s45
	s_cmp_eq_u32 s82, s89
	s_cselect_b32 s45, s39, s46
	s_cselect_b32 s44, s93, s36
	s_cselect_b32 s47, s90, s13
	s_cselect_b32 s46, s97, s12
	s_cselect_b32 vcc_hi, s96, vcc_hi
	s_cselect_b32 vcc_lo, s50, vcc_lo
	s_mov_b32 m0, s64
	v_lshl_add_u64 v[224:225], vcc, 0, v[216:217]
	v_lshl_add_u64 v[226:227], vcc, 0, v[220:221]
	s_add_u32 vcc_lo, vcc_lo, s8
	ds_read_b128 v[198:201], v249 offset:16384
	ds_read_b128 v[202:205], v249 offset:17408
	ds_read_b128 v[190:193], v249 offset:18432
	ds_read_b128 v[194:197], v249 offset:19456
	ds_read_b128 v[182:185], v249 offset:20480
	ds_read_b128 v[186:189], v249 offset:21504
	ds_read_b128 v[174:177], v249 offset:22528
	ds_read_b128 v[178:181], v249 offset:23552
	global_load_lds_dwordx4 v[224:225], off
	s_mov_b32 m0, s65
	s_addc_u32 vcc_hi, vcc_hi, s9
	global_load_lds_dwordx4 v[226:227], off
	v_lshl_add_u64 v[228:229], vcc, 0, v[216:217]
	s_mov_b32 m0, s67
	v_lshl_add_u64 v[230:231], vcc, 0, v[220:221]
	global_load_lds_dwordx4 v216, vcc
	s_mov_b32 m0, s68
	v_lshl_add_u64 v[232:233], s[44:45], 0, v[214:215]
	global_load_lds_dwordx4 v220, vcc
	s_mov_b32 m0, s63
	v_lshl_add_u64 v[234:235], s[44:45], 0, v[218:219]
	global_load_lds_dwordx4 v214, s[44:45]
	s_mov_b32 m0, s69
	v_lshl_add_u64 v[4:5], s[46:47], 0, v[222:223]
	global_load_lds_dwordx4 v218, s[44:45]
	s_and_saveexec_b64 s[46:47], s[2:3]
	s_cbranch_execz .LBB0_1660
	s_add_i32 s12, s60, 0
	s_add_i32 m0, s12, 0x22400
	s_nop 0
	global_load_lds_dwordx4 v[4:5], off
; #define PG8_LDX(b) do { if constexpr (XR) { _Pragma("unroll") for (int k = 0; k < 2; ++k) Ax_[k] = *(const PG8_LAS bf16x8*)(lds + XR_OFF + (b) * 2048 + aoffx + k * 1024); } } while (0)
; #define PG8_MMAX() do { if constexpr (XR) { if (hasx) { __builtin_amdgcn_s_setprio(1); if (wr == 0) PG8_MMAX_(B0); else PG8_MMAX_(B1); __builtin_amdgcn_s_setprio(0); } } } while (0)
; #define PG8_WAIT_LOOP() do { if constexpr (XR) PG8_WAIT_V(9); else PG8_WAIT_V(8); } while (0)
; #define PG8_STAGE(bufoff, gbase, voff) do { _Pragma("unroll") for (int _i = 0; _i < 2; ++_i) \
;         __builtin_amdgcn_global_load_lds((const unsigned*)((const char*)(gbase) + (voff)[_i]), (PG8_LAS unsigned*)(lds + (bufoff) + ldsw + _i * 8192), 16, 0, 0); } while (0)
; #define PG8_LDA(dst, b, h) do { _Pragma("unroll") for (int m = 0; m < 4; ++m) _Pragma("unroll") for (int k = 0; k < 2; ++k) dst[m][k] = *(const PG8_LAS bf16x8*)(lds + PG8_SA(b, h) + aoff + m * 2048 + k * 1024); } while (0)
; #define PG8_LDB(dst, b, h) do { _Pragma("unroll") for (int n = 0; n < 2; ++n) _Pragma("unroll") for (int k = 0; k < 2; ++k) dst[n][k] = *(const PG8_LAS bf16x8*)(lds + PG8_SB(b, h) + boff + n * 2048 + k * 1024); } while (0)
; #define PG8_MMA(ai, bj, At, Bt) do { __builtin_amdgcn_s_setprio(1); _Pragma("unroll") for (int m = 0; m < 4; ++m) _Pragma("unroll") for (int n = 0; n < 2; ++n) _Pragma("unroll") for (int k = 0; k < 2; ++k) \
;         acc[ai][bj][m][n] = __builtin_amdgcn_mfma_f32_16x16x32_bf16(Bt[n][k], At[m][k], acc[ai][bj][m][n], 0, 0, 0); __builtin_amdgcn_s_setprio(0); } while (0)
; #define PG8_WAIT_L(n) asm volatile("s_waitcnt lgkmcnt(" #n ")" ::: "memory")
; #define PG8_BAR __builtin_amdgcn_s_barrier()
; #define PG8_SCHED __builtin_amdgcn_sched_barrier(0)
; template <class Epi, class Sched, bool ALIGN_EPI = false, bool SP2 = false, bool DRAIN = true, bool XR = false>
; __device__ __forceinline__ void gemm_phase(PG8_LAS unsigned char* lds, const Gemm g, const Sched& S, const Epi& E) {
;     ...
;             PG8_WAIT_LOOP(); PG8_WAIT_L(0); PG8_BAR; PG8_MMA(1, 0, At, B0); PG8_MMA(1, 1, At, B1); PG8_BAR; PG8_SCHED;
;             PG8_LDB(B0, 1, 0); PG8_LDB(B1, 1, 1); PG8_SCHED; PG8_LDA(At, 1, 0); PG8_LDX(1); PG8_STAGE(PG8_SA(0, 1), a2 + hstepA, voffA);
;             PG8_WAIT_LOOP(); PG8_WAIT_L(0); PG8_BAR; PG8_MMA(0, 0, At, B0); PG8_MMA(0, 1, At, B1); PG8_MMAX(); PG8_BAR; PG8_SCHED;
.LBB0_1660:
	s_or_b64 exec, exec, s[46:47]
	s_waitcnt vmcnt(9)
	s_waitcnt lgkmcnt(0)
	s_barrier
	v_mfma_f32_16x16x32_bf16 v[74:77], v[158:161], v[198:201], v[74:77]
	v_mfma_f32_16x16x32_bf16 v[70:73], v[166:169], v[198:201], v[70:73]
	v_mfma_f32_16x16x32_bf16 v[58:61], v[158:161], v[190:193], v[58:61]
	v_mfma_f32_16x16x32_bf16 v[54:57], v[166:169], v[190:193], v[54:57]
	v_mfma_f32_16x16x32_bf16 v[42:45], v[158:161], v[182:185], v[42:45]
	v_mfma_f32_16x16x32_bf16 v[38:41], v[166:169], v[182:185], v[38:41]
	v_mfma_f32_16x16x32_bf16 v[26:29], v[158:161], v[174:177], v[26:29]
	v_mfma_f32_16x16x32_bf16 v[22:25], v[166:169], v[174:177], v[22:25]
	v_mfma_f32_16x16x32_bf16 v[74:77], v[162:165], v[202:205], v[74:77]
	v_mfma_f32_16x16x32_bf16 v[70:73], v[170:173], v[202:205], v[70:73]
	v_mfma_f32_16x16x32_bf16 v[58:61], v[162:165], v[194:197], v[58:61]
	v_mfma_f32_16x16x32_bf16 v[54:57], v[170:173], v[194:197], v[54:57]
	v_mfma_f32_16x16x32_bf16 v[42:45], v[162:165], v[186:189], v[42:45]
	v_mfma_f32_16x16x32_bf16 v[38:41], v[170:173], v[186:189], v[38:41]
	v_mfma_f32_16x16x32_bf16 v[26:29], v[162:165], v[178:181], v[26:29]
	v_mfma_f32_16x16x32_bf16 v[22:25], v[170:173], v[178:181], v[22:25]
	v_mfma_f32_16x16x32_bf16 v[66:69], v[142:145], v[198:201], v[66:69]
	v_mfma_f32_16x16x32_bf16 v[62:65], v[150:153], v[198:201], v[62:65]
	v_mfma_f32_16x16x32_bf16 v[50:53], v[142:145], v[190:193], v[50:53]
	v_mfma_f32_16x16x32_bf16 v[46:49], v[150:153], v[190:193], v[46:49]
	v_mfma_f32_16x16x32_bf16 v[34:37], v[142:145], v[182:185], v[34:37]
	v_mfma_f32_16x16x32_bf16 v[30:33], v[150:153], v[182:185], v[30:33]
	v_mfma_f32_16x16x32_bf16 v[18:21], v[142:145], v[174:177], v[18:21]
	v_mfma_f32_16x16x32_bf16 v[14:17], v[150:153], v[174:177], v[14:17]
	v_mfma_f32_16x16x32_bf16 v[66:69], v[146:149], v[202:205], v[66:69]
	v_mfma_f32_16x16x32_bf16 v[62:65], v[154:157], v[202:205], v[62:65]
	v_mfma_f32_16x16x32_bf16 v[50:53], v[146:149], v[194:197], v[50:53]
	v_mfma_f32_16x16x32_bf16 v[46:49], v[154:157], v[194:197], v[46:49]
	v_mfma_f32_16x16x32_bf16 v[34:37], v[146:149], v[186:189], v[34:37]
	v_mfma_f32_16x16x32_bf16 v[30:33], v[154:157], v[186:189], v[30:33]
	v_mfma_f32_16x16x32_bf16 v[18:21], v[146:149], v[178:181], v[18:21]
	v_mfma_f32_16x16x32_bf16 v[14:17], v[154:157], v[178:181], v[14:17]
	s_barrier
	v_add_u32_e32 v2, 0x18000, v248
	ds_read_b128 v[158:161], v2
	ds_read_b128 v[162:165], v2 offset:1024
	ds_read_b128 v[166:169], v2 offset:2048
	ds_read_b128 v[170:173], v2 offset:3072
	v_add_u32_e32 v2, 0x1c000, v248
	ds_read_b128 v[142:145], v2
	ds_read_b128 v[146:149], v2 offset:1024
	ds_read_b128 v[150:153], v2 offset:2048
	ds_read_b128 v[154:157], v2 offset:3072
	s_add_u32 s44, s44, 0x10000
	s_addc_u32 s45, s45, 0
	s_mov_b32 m0, s72
	v_add_u32_e32 v2, 0x22c00, v250
	ds_read_b128 v[182:185], v249 offset:32768
	ds_read_b128 v[186:189], v249 offset:33792
	ds_read_b128 v[190:193], v249 offset:34816
	ds_read_b128 v[194:197], v249 offset:35840
	ds_read_b128 v[198:201], v249 offset:36864
	ds_read_b128 v[202:205], v249 offset:37888
	ds_read_b128 v[206:209], v249 offset:38912
	ds_read_b128 v[240:243], v249 offset:39936
	ds_read_b128 v[174:177], v2
	ds_read_b128 v[178:181], v2 offset:1024
	global_load_lds_dwordx4 v214, s[44:45]
	s_mov_b32 m0, s73
	s_nop 0
	global_load_lds_dwordx4 v218, s[44:45]
	s_waitcnt vmcnt(9)
	s_waitcnt lgkmcnt(0)
	s_barrier
	v_mfma_f32_16x16x32_bf16 v[138:141], v[158:161], v[182:185], v[138:141]
	v_mfma_f32_16x16x32_bf16 v[134:137], v[166:169], v[182:185], v[134:137]
	v_mfma_f32_16x16x32_bf16 v[122:125], v[158:161], v[190:193], v[122:125]
	v_mfma_f32_16x16x32_bf16 v[118:121], v[166:169], v[190:193], v[118:121]
	v_mfma_f32_16x16x32_bf16 v[106:109], v[158:161], v[198:201], v[106:109]
	v_mfma_f32_16x16x32_bf16 v[102:105], v[166:169], v[198:201], v[102:105]
	v_mfma_f32_16x16x32_bf16 v[90:93], v[158:161], v[206:209], v[90:93]
	v_mfma_f32_16x16x32_bf16 v[86:89], v[166:169], v[206:209], v[86:89]
	v_mfma_f32_16x16x32_bf16 v[138:141], v[162:165], v[186:189], v[138:141]
	v_mfma_f32_16x16x32_bf16 v[134:137], v[170:173], v[186:189], v[134:137]
	v_mfma_f32_16x16x32_bf16 v[122:125], v[162:165], v[194:197], v[122:125]
	v_mfma_f32_16x16x32_bf16 v[118:121], v[170:173], v[194:197], v[118:121]
	v_mfma_f32_16x16x32_bf16 v[106:109], v[162:165], v[202:205], v[106:109]
	v_mfma_f32_16x16x32_bf16 v[102:105], v[170:173], v[202:205], v[102:105]
	v_mfma_f32_16x16x32_bf16 v[90:93], v[162:165], v[240:243], v[90:93]
	v_mfma_f32_16x16x32_bf16 v[86:89], v[170:173], v[240:243], v[86:89]
	v_mfma_f32_16x16x32_bf16 v[130:133], v[142:145], v[182:185], v[130:133]
	v_mfma_f32_16x16x32_bf16 v[126:129], v[150:153], v[182:185], v[126:129]
	v_mfma_f32_16x16x32_bf16 v[114:117], v[142:145], v[190:193], v[114:117]
	v_mfma_f32_16x16x32_bf16 v[110:113], v[150:153], v[190:193], v[110:113]
	v_mfma_f32_16x16x32_bf16 v[98:101], v[142:145], v[198:201], v[98:101]
	v_mfma_f32_16x16x32_bf16 v[94:97], v[150:153], v[198:201], v[94:97]
	v_mfma_f32_16x16x32_bf16 v[82:85], v[142:145], v[206:209], v[82:85]
	v_mfma_f32_16x16x32_bf16 v[78:81], v[150:153], v[206:209], v[78:81]
	v_mfma_f32_16x16x32_bf16 v[130:133], v[146:149], v[186:189], v[130:133]
	v_mfma_f32_16x16x32_bf16 v[126:129], v[154:157], v[186:189], v[126:129]
	v_mfma_f32_16x16x32_bf16 v[114:117], v[146:149], v[194:197], v[114:117]
	v_mfma_f32_16x16x32_bf16 v[110:113], v[154:157], v[194:197], v[110:113]
	v_mfma_f32_16x16x32_bf16 v[98:101], v[146:149], v[202:205], v[98:101]
	v_mfma_f32_16x16x32_bf16 v[94:97], v[154:157], v[202:205], v[94:97]
	v_mfma_f32_16x16x32_bf16 v[82:85], v[146:149], v[240:243], v[82:85]
	v_mfma_f32_16x16x32_bf16 v[78:81], v[154:157], v[240:243], v[78:81]
	s_and_b64 vcc, exec, s[6:7]
	s_cbranch_vccnz .LBB0_1666
	s_and_b64 vcc, exec, s[0:1]
	s_mov_b64 s[0:1], -1
	s_cbranch_vccnz .LBB0_1663
	v_mfma_f32_16x16x32_bf16 v[10:13], v[142:145], v[174:177], v[10:13]
	s_mov_b64 s[0:1], 0
	v_mfma_f32_16x16x32_bf16 v[6:9], v[150:153], v[174:177], v[6:9]
	v_mfma_f32_16x16x32_bf16 v[10:13], v[146:149], v[178:181], v[10:13]
	v_mfma_f32_16x16x32_bf16 v[6:9], v[154:157], v[178:181], v[6:9]

; #define PG8_STAGEX(b, gbase) do { if constexpr (XR) { if (lane < 16) __builtin_amdgcn_global_load_lds((const unsigned*)((const char*)(gbase) + voffX), (PG8_LAS unsigned*)(lds + XR_OFF + (b) * 2048 + wid * 256), 16, 0, 0); } } while (0)
; #define PG8_MMAX() do { if constexpr (XR) { if (hasx) { __builtin_amdgcn_s_setprio(1); if (wr == 0) PG8_MMAX_(B0); else PG8_MMAX_(B1); __builtin_amdgcn_s_setprio(0); } } } while (0)
; #define PG8_WAIT_LOOP() do { if constexpr (XR) PG8_WAIT_V(9); else PG8_WAIT_V(8); } while (0)
; #define PG8_STAGE(bufoff, gbase, voff) do { _Pragma("unroll") for (int _i = 0; _i < 2; ++_i) \
;         __builtin_amdgcn_global_load_lds((const unsigned*)((const char*)(gbase) + (voff)[_i]), (PG8_LAS unsigned*)(lds + (bufoff) + ldsw + _i * 8192), 16, 0, 0); } while (0)
; #define PG8_LDA(dst, b, h) do { _Pragma("unroll") for (int m = 0; m < 4; ++m) _Pragma("unroll") for (int k = 0; k < 2; ++k) dst[m][k] = *(const PG8_LAS bf16x8*)(lds + PG8_SA(b, h) + aoff + m * 2048 + k * 1024); } while (0)
; #define PG8_MMA(ai, bj, At, Bt) do { __builtin_amdgcn_s_setprio(1); _Pragma("unroll") for (int m = 0; m < 4; ++m) _Pragma("unroll") for (int n = 0; n < 2; ++n) _Pragma("unroll") for (int k = 0; k < 2; ++k) \
;         acc[ai][bj][m][n] = __builtin_amdgcn_mfma_f32_16x16x32_bf16(Bt[n][k], At[m][k], acc[ai][bj][m][n], 0, 0, 0); __builtin_amdgcn_s_setprio(0); } while (0)
; #define PG8_WAIT_L(n) asm volatile("s_waitcnt lgkmcnt(" #n ")" ::: "memory")
; #define PG8_BAR __builtin_amdgcn_s_barrier()
; #define PG8_SCHED __builtin_amdgcn_sched_barrier(0)
; template <class Epi, class Sched, bool ALIGN_EPI = false, bool SP2 = false, bool DRAIN = true, bool XR = false>
; __device__ __forceinline__ void gemm_phase(PG8_LAS unsigned char* lds, const Gemm g, const Sched& S, const Epi& E) {
;     ...
;             PG8_WAIT_LOOP(); PG8_WAIT_L(0); PG8_BAR; PG8_MMA(0, 0, At, B0); PG8_MMA(0, 1, At, B1); PG8_MMAX(); PG8_BAR; PG8_SCHED;
;             PG8_LDA(At, 1, 1); PG8_STAGE(PG8_SB(1, 0), b3, voffB); PG8_STAGE(PG8_SB(1, 1), b3 + hstep, voffB); PG8_STAGE(PG8_SA(1, 0), a3, voffA); PG8_STAGEX(1, x3);
.LBB0_1665:
.LBB0_1666:
	s_barrier
	s_mov_b32 m0, s74
	v_lshl_add_u64 v[206:207], v[224:225], 0, s[86:87]
	ds_read_b128 v[198:201], v249 offset:49152
	ds_read_b128 v[202:205], v249 offset:50176
	ds_read_b128 v[190:193], v249 offset:51200
	ds_read_b128 v[194:197], v249 offset:52224
	ds_read_b128 v[182:185], v249 offset:53248
	ds_read_b128 v[186:189], v249 offset:54272
	ds_read_b128 v[174:177], v249 offset:55296
	ds_read_b128 v[178:181], v249 offset:56320
	global_load_lds_dwordx4 v[206:207], off
	v_lshl_add_u64 v[206:207], v[226:227], 0, s[86:87]
	s_mov_b32 m0, s75
	s_nop 0
	global_load_lds_dwordx4 v[206:207], off
	v_lshl_add_u64 v[206:207], v[228:229], 0, s[86:87]
	s_mov_b32 m0, s78
	s_nop 0
	global_load_lds_dwordx4 v[206:207], off
	v_lshl_add_u64 v[206:207], v[230:231], 0, s[86:87]
	s_mov_b32 m0, s79
	s_nop 0
	global_load_lds_dwordx4 v[206:207], off
	v_lshl_add_u64 v[206:207], v[232:233], 0, s[86:87]
	s_mov_b32 m0, s76
	s_nop 0
	global_load_lds_dwordx4 v[206:207], off
	v_lshl_add_u64 v[206:207], v[234:235], 0, s[86:87]
	s_mov_b32 m0, s77
	s_nop 0
	global_load_lds_dwordx4 v[206:207], off
	s_and_saveexec_b64 s[0:1], s[2:3]
	s_cbranch_execz .LBB0_1651
	s_add_i32 s6, s60, 0
	v_lshl_add_u64 v[4:5], v[4:5], 0, s[86:87]
	s_add_i32 m0, s6, 0x22c00
	s_nop 0
	global_load_lds_dwordx4 v[4:5], off
	s_branch .LBB0_1651

; #define PG8_LDX(b) do { if constexpr (XR) { _Pragma("unroll") for (int k = 0; k < 2; ++k) Ax_[k] = *(const PG8_LAS bf16x8*)(lds + XR_OFF + (b) * 2048 + aoffx + k * 1024); } } while (0)
; #define PG8_MMAX() do { if constexpr (XR) { if (hasx) { __builtin_amdgcn_s_setprio(1); if (wr == 0) PG8_MMAX_(B0); else PG8_MMAX_(B1); __builtin_amdgcn_s_setprio(0); } } } while (0)
; #define PG8_WAIT_LOOP() do { if constexpr (XR) PG8_WAIT_V(9); else PG8_WAIT_V(8); } while (0)
; #define PG8_STAGE(bufoff, gbase, voff) do { _Pragma("unroll") for (int _i = 0; _i < 2; ++_i) \
;         __builtin_amdgcn_global_load_lds((const unsigned*)((const char*)(gbase) + (voff)[_i]), (PG8_LAS unsigned*)(lds + (bufoff) + ldsw + _i * 8192), 16, 0, 0); } while (0)
; #define PG8_LDA(dst, b, h) do { _Pragma("unroll") for (int m = 0; m < 4; ++m) _Pragma("unroll") for (int k = 0; k < 2; ++k) dst[m][k] = *(const PG8_LAS bf16x8*)(lds + PG8_SA(b, h) + aoff + m * 2048 + k * 1024); } while (0)
; #define PG8_LDB(dst, b, h) do { _Pragma("unroll") for (int n = 0; n < 2; ++n) _Pragma("unroll") for (int k = 0; k < 2; ++k) dst[n][k] = *(const PG8_LAS bf16x8*)(lds + PG8_SB(b, h) + boff + n * 2048 + k * 1024); } while (0)
; #define PG8_MMA(ai, bj, At, Bt) do { __builtin_amdgcn_s_setprio(1); _Pragma("unroll") for (int m = 0; m < 4; ++m) _Pragma("unroll") for (int n = 0; n < 2; ++n) _Pragma("unroll") for (int k = 0; k < 2; ++k) \
;         acc[ai][bj][m][n] = __builtin_amdgcn_mfma_f32_16x16x32_bf16(Bt[n][k], At[m][k], acc[ai][bj][m][n], 0, 0, 0); __builtin_amdgcn_s_setprio(0); } while (0)
; #define PG8_WAIT_L(n) asm volatile("s_waitcnt lgkmcnt(" #n ")" ::: "memory")
; #define PG8_BAR __builtin_amdgcn_s_barrier()
; #define PG8_SCHED __builtin_amdgcn_sched_barrier(0)
; template <class Epi, class Sched, bool ALIGN_EPI = false, bool SP2 = false, bool DRAIN = true, bool XR = false>
; __device__ __forceinline__ void gemm_phase(PG8_LAS unsigned char* lds, const Gemm g, const Sched& S, const Epi& E) {
;     ...
;             const char* a1 = cA + PG8_KOA(t) + kstep;
;     ...
;             PG8_LDB(B0, 0, 0); PG8_LDB(B1, 0, 1); PG8_SCHED; PG8_LDA(At, 0, 0); PG8_LDX(0); PG8_STAGE(PG8_SA(1, 1), a1 + hstepA, voffA);
;             PG8_WAIT_LOOP(); PG8_WAIT_L(0); PG8_BAR; PG8_MMA(0, 0, At, B0); PG8_MMA(0, 1, At, B1); PG8_MMAX(); PG8_BAR; PG8_SCHED;
.LBB0_1856:
	v_add_u32_e32 v2, 0x10000, v237
	s_add_i32 s56, s88, s45
	ds_read_b128 v[158:161], v2
	ds_read_b128 v[162:165], v2 offset:1024
	ds_read_b128 v[166:169], v2 offset:2048
	ds_read_b128 v[170:173], v2 offset:3072
	v_add_u32_e32 v2, 0x14000, v237
	s_and_b32 s8, s56, s67
	ds_read_b128 v[142:145], v2
	ds_read_b128 v[146:149], v2 offset:1024
	ds_read_b128 v[150:153], v2 offset:2048
	ds_read_b128 v[154:157], v2 offset:3072
	s_lshr_b32 s84, s8, 2
	s_lshl_b32 s8, s8, 7
	s_lshl_b64 s[0:1], s[84:85], 9
	s_and_b32 s8, s8, 0x100
	s_add_u32 s0, s24, s0
	s_addc_u32 s1, s25, s1
	s_add_u32 s0, s0, s8
	s_addc_u32 s1, s1, 0
	s_add_u32 s0, s0, s18
	s_addc_u32 s1, s1, s19
	v_lshl_add_u64 v[4:5], s[0:1], 0, v[214:215]
	v_add_u32_e32 v2, 0x22400, v239
	v_lshl_add_u64 v[4:5], v[4:5], 0, s[86:87]
	s_add_i32 m0, s72, 0xc000
	ds_read_b128 v[182:185], v238
	ds_read_b128 v[186:189], v238 offset:1024
	ds_read_b128 v[190:193], v238 offset:2048
	ds_read_b128 v[194:197], v238 offset:3072
	ds_read_b128 v[198:201], v238 offset:4096
	ds_read_b128 v[202:205], v238 offset:5120
	ds_read_b128 v[206:209], v238 offset:6144
	ds_read_b128 v[224:227], v238 offset:7168
	ds_read_b128 v[174:177], v2
	ds_read_b128 v[178:181], v2 offset:1024
	global_load_lds_dwordx4 v[4:5], off
	v_lshl_add_u64 v[4:5], s[0:1], 0, v[218:219]
	v_lshl_add_u64 v[4:5], v[4:5], 0, s[86:87]
	s_add_i32 m0, s72, 0xe000
	s_nop 0
	global_load_lds_dwordx4 v[4:5], off
	s_waitcnt vmcnt(9)
	s_waitcnt lgkmcnt(0)
	s_barrier
	v_mfma_f32_16x16x32_bf16 v[138:141], v[158:161], v[182:185], v[138:141]
	v_mfma_f32_16x16x32_bf16 v[134:137], v[166:169], v[182:185], v[134:137]
	v_mfma_f32_16x16x32_bf16 v[130:133], v[158:161], v[190:193], v[130:133]
	v_mfma_f32_16x16x32_bf16 v[126:129], v[166:169], v[190:193], v[126:129]
	v_mfma_f32_16x16x32_bf16 v[122:125], v[158:161], v[198:201], v[122:125]
	v_mfma_f32_16x16x32_bf16 v[118:121], v[166:169], v[198:201], v[118:121]
	v_mfma_f32_16x16x32_bf16 v[114:117], v[158:161], v[206:209], v[114:117]
	v_mfma_f32_16x16x32_bf16 v[110:113], v[166:169], v[206:209], v[110:113]
	v_mfma_f32_16x16x32_bf16 v[138:141], v[162:165], v[186:189], v[138:141]
	v_mfma_f32_16x16x32_bf16 v[134:137], v[170:173], v[186:189], v[134:137]
	v_mfma_f32_16x16x32_bf16 v[130:133], v[162:165], v[194:197], v[130:133]
	v_mfma_f32_16x16x32_bf16 v[126:129], v[170:173], v[194:197], v[126:129]
	v_mfma_f32_16x16x32_bf16 v[122:125], v[162:165], v[202:205], v[122:125]
	v_mfma_f32_16x16x32_bf16 v[118:121], v[170:173], v[202:205], v[118:121]
	v_mfma_f32_16x16x32_bf16 v[114:117], v[162:165], v[224:227], v[114:117]
	v_mfma_f32_16x16x32_bf16 v[110:113], v[170:173], v[224:227], v[110:113]
	v_mfma_f32_16x16x32_bf16 v[106:109], v[142:145], v[182:185], v[106:109]
	v_mfma_f32_16x16x32_bf16 v[102:105], v[150:153], v[182:185], v[102:105]
	v_mfma_f32_16x16x32_bf16 v[98:101], v[142:145], v[190:193], v[98:101]
	v_mfma_f32_16x16x32_bf16 v[94:97], v[150:153], v[190:193], v[94:97]
	v_mfma_f32_16x16x32_bf16 v[90:93], v[142:145], v[198:201], v[90:93]
	v_mfma_f32_16x16x32_bf16 v[86:89], v[150:153], v[198:201], v[86:89]
	v_mfma_f32_16x16x32_bf16 v[82:85], v[142:145], v[206:209], v[82:85]
	v_mfma_f32_16x16x32_bf16 v[78:81], v[150:153], v[206:209], v[78:81]
	v_mfma_f32_16x16x32_bf16 v[106:109], v[146:149], v[186:189], v[106:109]
	v_mfma_f32_16x16x32_bf16 v[102:105], v[154:157], v[186:189], v[102:105]
	v_mfma_f32_16x16x32_bf16 v[98:101], v[146:149], v[194:197], v[98:101]
	v_mfma_f32_16x16x32_bf16 v[94:97], v[154:157], v[194:197], v[94:97]
	v_mfma_f32_16x16x32_bf16 v[90:93], v[146:149], v[202:205], v[90:93]
	v_mfma_f32_16x16x32_bf16 v[86:89], v[154:157], v[202:205], v[86:89]
	v_mfma_f32_16x16x32_bf16 v[82:85], v[146:149], v[224:227], v[82:85]
	v_mfma_f32_16x16x32_bf16 v[78:81], v[154:157], v[224:227], v[78:81]
	v_cndmask_b32_e64 v2, 0, 1, s[40:41]
	v_cmp_ne_u32_e64 s[8:9], 1, v2
	v_cndmask_b32_e64 v2, 0, 1, s[46:47]
	s_andn2_b64 vcc, exec, s[40:41]
	v_cmp_ne_u32_e64 s[0:1], 1, v2
	s_cbranch_vccnz .LBB0_1862
	s_and_b64 vcc, exec, s[0:1]
	s_mov_b64 s[54:55], -1
	s_cbranch_vccnz .LBB0_1859
	v_mfma_f32_16x16x32_bf16 v[10:13], v[142:145], v[174:177], v[10:13]
	s_mov_b64 s[54:55], 0
	v_mfma_f32_16x16x32_bf16 v[6:9], v[150:153], v[174:177], v[6:9]
	v_mfma_f32_16x16x32_bf16 v[10:13], v[146:149], v[178:181], v[10:13]
	v_mfma_f32_16x16x32_bf16 v[6:9], v[154:157], v[178:181], v[6:9]

; #define PG8_STAGEX(b, gbase) do { if constexpr (XR) { if (lane < 16) __builtin_amdgcn_global_load_lds((const unsigned*)((const char*)(gbase) + voffX), (PG8_LAS unsigned*)(lds + XR_OFF + (b) * 2048 + wid * 256), 16, 0, 0); } } while (0)
; #define PG8_MMAX() do { if constexpr (XR) { if (hasx) { __builtin_amdgcn_s_setprio(1); if (wr == 0) PG8_MMAX_(B0); else PG8_MMAX_(B1); __builtin_amdgcn_s_setprio(0); } } } while (0)
; #define PG8_WAIT_LOOP() do { if constexpr (XR) PG8_WAIT_V(9); else PG8_WAIT_V(8); } while (0)
; #define PG8_STAGE(bufoff, gbase, voff) do { _Pragma("unroll") for (int _i = 0; _i < 2; ++_i) \
;         __builtin_amdgcn_global_load_lds((const unsigned*)((const char*)(gbase) + (voff)[_i]), (PG8_LAS unsigned*)(lds + (bufoff) + ldsw + _i * 8192), 16, 0, 0); } while (0)
; #define PG8_LDA(dst, b, h) do { _Pragma("unroll") for (int m = 0; m < 4; ++m) _Pragma("unroll") for (int k = 0; k < 2; ++k) dst[m][k] = *(const PG8_LAS bf16x8*)(lds + PG8_SA(b, h) + aoff + m * 2048 + k * 1024); } while (0)
; #define PG8_MMA(ai, bj, At, Bt) do { __builtin_amdgcn_s_setprio(1); _Pragma("unroll") for (int m = 0; m < 4; ++m) _Pragma("unroll") for (int n = 0; n < 2; ++n) _Pragma("unroll") for (int k = 0; k < 2; ++k) \
;         acc[ai][bj][m][n] = __builtin_amdgcn_mfma_f32_16x16x32_bf16(Bt[n][k], At[m][k], acc[ai][bj][m][n], 0, 0, 0); __builtin_amdgcn_s_setprio(0); } while (0)
; #define PG8_WAIT_L(n) asm volatile("s_waitcnt lgkmcnt(" #n ")" ::: "memory")
; #define PG8_BAR __builtin_amdgcn_s_barrier()
; template <class Epi, class Sched, bool ALIGN_EPI = false, bool SP2 = false, bool DRAIN = true, bool XR = false>
; __device__ __forceinline__ void gemm_phase(PG8_LAS unsigned char* lds, const Gemm g, const Sched& S, const Epi& E) {
;     ...
;             const char* a2 = last ? nA + ka0 : cA + PG8_KOA(t + 2); const char* b2 = last ? nB + kb0 : cB + PG8_KOB(t + 2);
;             const char* x2 = XR ? (last ? nX + kx0 : cX + PG8_KOX(t + 2)) : nullptr; const char* x3 = XR ? x2 + kstep : nullptr;
;             const char* a3 = a2 + kstep; const char* b3 = b2 + kstep;
;     ...
;             PG8_WAIT_LOOP(); PG8_WAIT_L(0); PG8_BAR; PG8_MMA(0, 0, At, B0); PG8_MMA(0, 1, At, B1); PG8_MMAX(); PG8_BAR; PG8_SCHED;
;             PG8_LDA(At, 0, 1); PG8_STAGE(PG8_SB(0, 0), b2, voffB); PG8_STAGE(PG8_SB(0, 1), b2 + hstep, voffB); PG8_STAGE(PG8_SA(0, 0), a2, voffA); PG8_STAGEX(0, x2);
.LBB0_1861:
.LBB0_1862:
	s_barrier
	s_add_i32 s56, s56, 2
	s_and_b32 s54, s56, s67
	s_lshr_b32 s84, s54, 2
	s_lshl_b32 s36, s54, 7
	s_lshl_b64 s[56:57], s[84:85], 9
	s_and_b32 s36, s36, 0x100
	s_add_u32 s55, s24, s56
	s_addc_u32 s56, s25, s57
	s_add_u32 s36, s55, s36
	s_mov_b32 s55, s85
	s_addc_u32 s56, s56, 0
	s_lshl_b64 s[54:55], s[54:55], 7
	s_add_u32 vcc_lo, s22, s54
	s_addc_u32 vcc_hi, s23, s55
	s_add_u32 s70, s28, s54
	s_addc_u32 s57, s29, s55
	s_cmp_eq_u32 s63, s45
	s_cselect_b32 s55, s59, s56
	s_cselect_b32 s54, s58, s36
	s_cselect_b32 s57, s44, s57
	s_cselect_b32 s56, s43, s70
	s_cselect_b32 vcc_hi, s42, vcc_hi
	s_cselect_b32 vcc_lo, s78, vcc_lo
	s_mov_b32 m0, s73
	v_lshl_add_u64 v[224:225], vcc, 0, v[216:217]
	v_lshl_add_u64 v[226:227], vcc, 0, v[220:221]
	s_add_u32 vcc_lo, vcc_lo, s18
	ds_read_b128 v[198:201], v238 offset:16384
	ds_read_b128 v[202:205], v238 offset:17408
	ds_read_b128 v[190:193], v238 offset:18432
	ds_read_b128 v[194:197], v238 offset:19456
	ds_read_b128 v[182:185], v238 offset:20480
	ds_read_b128 v[186:189], v238 offset:21504
	ds_read_b128 v[174:177], v238 offset:22528
	ds_read_b128 v[178:181], v238 offset:23552
	global_load_lds_dwordx4 v[224:225], off
	s_mov_b32 m0, s74
	s_addc_u32 vcc_hi, vcc_hi, s19
	global_load_lds_dwordx4 v[226:227], off
	v_lshl_add_u64 v[228:229], vcc, 0, v[216:217]
	s_mov_b32 m0, s75
	v_lshl_add_u64 v[230:231], vcc, 0, v[220:221]
	global_load_lds_dwordx4 v216, vcc
	s_mov_b32 m0, s76
	v_lshl_add_u64 v[232:233], s[54:55], 0, v[214:215]
	global_load_lds_dwordx4 v220, vcc
	s_mov_b32 m0, s72
	v_lshl_add_u64 v[234:235], s[54:55], 0, v[218:219]
	global_load_lds_dwordx4 v214, s[54:55]
	s_mov_b32 m0, s77
	v_lshl_add_u64 v[4:5], s[56:57], 0, v[222:223]
	global_load_lds_dwordx4 v218, s[54:55]
	s_and_saveexec_b64 s[56:57], s[2:3]
	s_cbranch_execz .LBB0_1864
	s_add_i32 s36, s68, 0
	s_add_i32 m0, s36, 0x22400
	s_nop 0
	global_load_lds_dwordx4 v[4:5], off
; #define PG8_LDX(b) do { if constexpr (XR) { _Pragma("unroll") for (int k = 0; k < 2; ++k) Ax_[k] = *(const PG8_LAS bf16x8*)(lds + XR_OFF + (b) * 2048 + aoffx + k * 1024); } } while (0)
; #define PG8_MMAX() do { if constexpr (XR) { if (hasx) { __builtin_amdgcn_s_setprio(1); if (wr == 0) PG8_MMAX_(B0); else PG8_MMAX_(B1); __builtin_amdgcn_s_setprio(0); } } } while (0)
; #define PG8_WAIT_LOOP() do { if constexpr (XR) PG8_WAIT_V(9); else PG8_WAIT_V(8); } while (0)
; #define PG8_STAGE(bufoff, gbase, voff) do { _Pragma("unroll") for (int _i = 0; _i < 2; ++_i) \
;         __builtin_amdgcn_global_load_lds((const unsigned*)((const char*)(gbase) + (voff)[_i]), (PG8_LAS unsigned*)(lds + (bufoff) + ldsw + _i * 8192), 16, 0, 0); } while (0)
; #define PG8_LDA(dst, b, h) do { _Pragma("unroll") for (int m = 0; m < 4; ++m) _Pragma("unroll") for (int k = 0; k < 2; ++k) dst[m][k] = *(const PG8_LAS bf16x8*)(lds + PG8_SA(b, h) + aoff + m * 2048 + k * 1024); } while (0)
; #define PG8_LDB(dst, b, h) do { _Pragma("unroll") for (int n = 0; n < 2; ++n) _Pragma("unroll") for (int k = 0; k < 2; ++k) dst[n][k] = *(const PG8_LAS bf16x8*)(lds + PG8_SB(b, h) + boff + n * 2048 + k * 1024); } while (0)
; #define PG8_MMA(ai, bj, At, Bt) do { __builtin_amdgcn_s_setprio(1); _Pragma("unroll") for (int m = 0; m < 4; ++m) _Pragma("unroll") for (int n = 0; n < 2; ++n) _Pragma("unroll") for (int k = 0; k < 2; ++k) \
;         acc[ai][bj][m][n] = __builtin_amdgcn_mfma_f32_16x16x32_bf16(Bt[n][k], At[m][k], acc[ai][bj][m][n], 0, 0, 0); __builtin_amdgcn_s_setprio(0); } while (0)
; #define PG8_WAIT_L(n) asm volatile("s_waitcnt lgkmcnt(" #n ")" ::: "memory")
; #define PG8_BAR __builtin_amdgcn_s_barrier()
; #define PG8_SCHED __builtin_amdgcn_sched_barrier(0)
; template <class Epi, class Sched, bool ALIGN_EPI = false, bool SP2 = false, bool DRAIN = true, bool XR = false>
; __device__ __forceinline__ void gemm_phase(PG8_LAS unsigned char* lds, const Gemm g, const Sched& S, const Epi& E) {
;     ...
;             PG8_WAIT_LOOP(); PG8_WAIT_L(0); PG8_BAR; PG8_MMA(1, 0, At, B0); PG8_MMA(1, 1, At, B1); PG8_BAR; PG8_SCHED;
;             PG8_LDB(B0, 1, 0); PG8_LDB(B1, 1, 1); PG8_SCHED; PG8_LDA(At, 1, 0); PG8_LDX(1); PG8_STAGE(PG8_SA(0, 1), a2 + hstepA, voffA);
;             PG8_WAIT_LOOP(); PG8_WAIT_L(0); PG8_BAR; PG8_MMA(0, 0, At, B0); PG8_MMA(0, 1, At, B1); PG8_MMAX(); PG8_BAR; PG8_SCHED;
.LBB0_1864:
	s_or_b64 exec, exec, s[56:57]
	s_waitcnt vmcnt(9)
	s_waitcnt lgkmcnt(0)
	s_barrier
	v_mfma_f32_16x16x32_bf16 v[74:77], v[158:161], v[198:201], v[74:77]
	v_mfma_f32_16x16x32_bf16 v[70:73], v[166:169], v[198:201], v[70:73]
	v_mfma_f32_16x16x32_bf16 v[66:69], v[158:161], v[190:193], v[66:69]
	v_mfma_f32_16x16x32_bf16 v[62:65], v[166:169], v[190:193], v[62:65]
	v_mfma_f32_16x16x32_bf16 v[58:61], v[158:161], v[182:185], v[58:61]
	v_mfma_f32_16x16x32_bf16 v[54:57], v[166:169], v[182:185], v[54:57]
	v_mfma_f32_16x16x32_bf16 v[50:53], v[158:161], v[174:177], v[50:53]
	v_mfma_f32_16x16x32_bf16 v[46:49], v[166:169], v[174:177], v[46:49]
	v_mfma_f32_16x16x32_bf16 v[74:77], v[162:165], v[202:205], v[74:77]
	v_mfma_f32_16x16x32_bf16 v[70:73], v[170:173], v[202:205], v[70:73]
	v_mfma_f32_16x16x32_bf16 v[66:69], v[162:165], v[194:197], v[66:69]
	v_mfma_f32_16x16x32_bf16 v[62:65], v[170:173], v[194:197], v[62:65]
	v_mfma_f32_16x16x32_bf16 v[58:61], v[162:165], v[186:189], v[58:61]
	v_mfma_f32_16x16x32_bf16 v[54:57], v[170:173], v[186:189], v[54:57]
	v_mfma_f32_16x16x32_bf16 v[50:53], v[162:165], v[178:181], v[50:53]
	v_mfma_f32_16x16x32_bf16 v[46:49], v[170:173], v[178:181], v[46:49]
	v_mfma_f32_16x16x32_bf16 v[42:45], v[142:145], v[198:201], v[42:45]
	v_mfma_f32_16x16x32_bf16 v[38:41], v[150:153], v[198:201], v[38:41]
	v_mfma_f32_16x16x32_bf16 v[34:37], v[142:145], v[190:193], v[34:37]
	v_mfma_f32_16x16x32_bf16 v[30:33], v[150:153], v[190:193], v[30:33]
	v_mfma_f32_16x16x32_bf16 v[26:29], v[142:145], v[182:185], v[26:29]
	v_mfma_f32_16x16x32_bf16 v[22:25], v[150:153], v[182:185], v[22:25]
	v_mfma_f32_16x16x32_bf16 v[18:21], v[142:145], v[174:177], v[18:21]
	v_mfma_f32_16x16x32_bf16 v[14:17], v[150:153], v[174:177], v[14:17]
	v_mfma_f32_16x16x32_bf16 v[42:45], v[146:149], v[202:205], v[42:45]
	v_mfma_f32_16x16x32_bf16 v[38:41], v[154:157], v[202:205], v[38:41]
	v_mfma_f32_16x16x32_bf16 v[34:37], v[146:149], v[194:197], v[34:37]
	v_mfma_f32_16x16x32_bf16 v[30:33], v[154:157], v[194:197], v[30:33]
	v_mfma_f32_16x16x32_bf16 v[26:29], v[146:149], v[186:189], v[26:29]
	v_mfma_f32_16x16x32_bf16 v[22:25], v[154:157], v[186:189], v[22:25]
	v_mfma_f32_16x16x32_bf16 v[18:21], v[146:149], v[178:181], v[18:21]
	v_mfma_f32_16x16x32_bf16 v[14:17], v[154:157], v[178:181], v[14:17]
	s_barrier
	v_add_u32_e32 v2, 0x18000, v237
	ds_read_b128 v[158:161], v2
	ds_read_b128 v[162:165], v2 offset:1024
	ds_read_b128 v[166:169], v2 offset:2048
	ds_read_b128 v[170:173], v2 offset:3072
	v_add_u32_e32 v2, 0x1c000, v237
	ds_read_b128 v[142:145], v2
	ds_read_b128 v[146:149], v2 offset:1024
	ds_read_b128 v[150:153], v2 offset:2048
	ds_read_b128 v[154:157], v2 offset:3072
	s_add_u32 s54, s54, s18
	s_addc_u32 s55, s55, s19
	s_mov_b32 m0, s79
	v_add_u32_e32 v2, 0x22c00, v239
	ds_read_b128 v[182:185], v238 offset:32768
	ds_read_b128 v[186:189], v238 offset:33792
	ds_read_b128 v[190:193], v238 offset:34816
	ds_read_b128 v[194:197], v238 offset:35840
	ds_read_b128 v[198:201], v238 offset:36864
	ds_read_b128 v[202:205], v238 offset:37888
	ds_read_b128 v[206:209], v238 offset:38912
	ds_read_b128 v[240:243], v238 offset:39936
	ds_read_b128 v[174:177], v2
	ds_read_b128 v[178:181], v2 offset:1024
	global_load_lds_dwordx4 v214, s[54:55]
	s_mov_b32 m0, s80
	s_nop 0
	global_load_lds_dwordx4 v218, s[54:55]
	s_waitcnt vmcnt(9)
	s_waitcnt lgkmcnt(0)
	s_barrier
	v_mfma_f32_16x16x32_bf16 v[138:141], v[158:161], v[182:185], v[138:141]
	v_mfma_f32_16x16x32_bf16 v[134:137], v[166:169], v[182:185], v[134:137]
	v_mfma_f32_16x16x32_bf16 v[130:133], v[158:161], v[190:193], v[130:133]
	v_mfma_f32_16x16x32_bf16 v[126:129], v[166:169], v[190:193], v[126:129]
	v_mfma_f32_16x16x32_bf16 v[122:125], v[158:161], v[198:201], v[122:125]
	v_mfma_f32_16x16x32_bf16 v[118:121], v[166:169], v[198:201], v[118:121]
	v_mfma_f32_16x16x32_bf16 v[114:117], v[158:161], v[206:209], v[114:117]
	v_mfma_f32_16x16x32_bf16 v[110:113], v[166:169], v[206:209], v[110:113]
	v_mfma_f32_16x16x32_bf16 v[138:141], v[162:165], v[186:189], v[138:141]
	v_mfma_f32_16x16x32_bf16 v[134:137], v[170:173], v[186:189], v[134:137]
	v_mfma_f32_16x16x32_bf16 v[130:133], v[162:165], v[194:197], v[130:133]
	v_mfma_f32_16x16x32_bf16 v[126:129], v[170:173], v[194:197], v[126:129]
	v_mfma_f32_16x16x32_bf16 v[122:125], v[162:165], v[202:205], v[122:125]
	v_mfma_f32_16x16x32_bf16 v[118:121], v[170:173], v[202:205], v[118:121]
	v_mfma_f32_16x16x32_bf16 v[114:117], v[162:165], v[240:243], v[114:117]
	v_mfma_f32_16x16x32_bf16 v[110:113], v[170:173], v[240:243], v[110:113]
	v_mfma_f32_16x16x32_bf16 v[106:109], v[142:145], v[182:185], v[106:109]
	v_mfma_f32_16x16x32_bf16 v[102:105], v[150:153], v[182:185], v[102:105]
	v_mfma_f32_16x16x32_bf16 v[98:101], v[142:145], v[190:193], v[98:101]
	v_mfma_f32_16x16x32_bf16 v[94:97], v[150:153], v[190:193], v[94:97]
	v_mfma_f32_16x16x32_bf16 v[90:93], v[142:145], v[198:201], v[90:93]
	v_mfma_f32_16x16x32_bf16 v[86:89], v[150:153], v[198:201], v[86:89]
	v_mfma_f32_16x16x32_bf16 v[82:85], v[142:145], v[206:209], v[82:85]
	v_mfma_f32_16x16x32_bf16 v[78:81], v[150:153], v[206:209], v[78:81]
	v_mfma_f32_16x16x32_bf16 v[106:109], v[146:149], v[186:189], v[106:109]
	v_mfma_f32_16x16x32_bf16 v[102:105], v[154:157], v[186:189], v[102:105]
	v_mfma_f32_16x16x32_bf16 v[98:101], v[146:149], v[194:197], v[98:101]
	v_mfma_f32_16x16x32_bf16 v[94:97], v[154:157], v[194:197], v[94:97]
	v_mfma_f32_16x16x32_bf16 v[90:93], v[146:149], v[202:205], v[90:93]
	v_mfma_f32_16x16x32_bf16 v[86:89], v[154:157], v[202:205], v[86:89]
	v_mfma_f32_16x16x32_bf16 v[82:85], v[146:149], v[240:243], v[82:85]
	v_mfma_f32_16x16x32_bf16 v[78:81], v[154:157], v[240:243], v[78:81]
	s_and_b64 vcc, exec, s[8:9]
	s_cbranch_vccnz .LBB0_1870
	s_and_b64 vcc, exec, s[0:1]
	s_mov_b64 s[0:1], -1
	s_cbranch_vccnz .LBB0_1867
	v_mfma_f32_16x16x32_bf16 v[10:13], v[142:145], v[174:177], v[10:13]
	s_mov_b64 s[0:1], 0
	v_mfma_f32_16x16x32_bf16 v[6:9], v[150:153], v[174:177], v[6:9]
	v_mfma_f32_16x16x32_bf16 v[10:13], v[146:149], v[178:181], v[10:13]
	v_mfma_f32_16x16x32_bf16 v[6:9], v[154:157], v[178:181], v[6:9]

; #define PG8_STAGEX(b, gbase) do { if constexpr (XR) { if (lane < 16) __builtin_amdgcn_global_load_lds((const unsigned*)((const char*)(gbase) + voffX), (PG8_LAS unsigned*)(lds + XR_OFF + (b) * 2048 + wid * 256), 16, 0, 0); } } while (0)
; #define PG8_MMAX() do { if constexpr (XR) { if (hasx) { __builtin_amdgcn_s_setprio(1); if (wr == 0) PG8_MMAX_(B0); else PG8_MMAX_(B1); __builtin_amdgcn_s_setprio(0); } } } while (0)
; #define PG8_WAIT_LOOP() do { if constexpr (XR) PG8_WAIT_V(9); else PG8_WAIT_V(8); } while (0)
; #define PG8_STAGE(bufoff, gbase, voff) do { _Pragma("unroll") for (int _i = 0; _i < 2; ++_i) \
;         __builtin_amdgcn_global_load_lds((const unsigned*)((const char*)(gbase) + (voff)[_i]), (PG8_LAS unsigned*)(lds + (bufoff) + ldsw + _i * 8192), 16, 0, 0); } while (0)
; #define PG8_LDA(dst, b, h) do { _Pragma("unroll") for (int m = 0; m < 4; ++m) _Pragma("unroll") for (int k = 0; k < 2; ++k) dst[m][k] = *(const PG8_LAS bf16x8*)(lds + PG8_SA(b, h) + aoff + m * 2048 + k * 1024); } while (0)
; #define PG8_MMA(ai, bj, At, Bt) do { __builtin_amdgcn_s_setprio(1); _Pragma("unroll") for (int m = 0; m < 4; ++m) _Pragma("unroll") for (int n = 0; n < 2; ++n) _Pragma("unroll") for (int k = 0; k < 2; ++k) \
;         acc[ai][bj][m][n] = __builtin_amdgcn_mfma_f32_16x16x32_bf16(Bt[n][k], At[m][k], acc[ai][bj][m][n], 0, 0, 0); __builtin_amdgcn_s_setprio(0); } while (0)
; #define PG8_WAIT_L(n) asm volatile("s_waitcnt lgkmcnt(" #n ")" ::: "memory")
; #define PG8_BAR __builtin_amdgcn_s_barrier()
; #define PG8_SCHED __builtin_amdgcn_sched_barrier(0)
; template <class Epi, class Sched, bool ALIGN_EPI = false, bool SP2 = false, bool DRAIN = true, bool XR = false>
; __device__ __forceinline__ void gemm_phase(PG8_LAS unsigned char* lds, const Gemm g, const Sched& S, const Epi& E) {
;     ...
;             PG8_WAIT_LOOP(); PG8_WAIT_L(0); PG8_BAR; PG8_MMA(0, 0, At, B0); PG8_MMA(0, 1, At, B1); PG8_MMAX(); PG8_BAR; PG8_SCHED;
;             PG8_LDA(At, 1, 1); PG8_STAGE(PG8_SB(1, 0), b3, voffB); PG8_STAGE(PG8_SB(1, 1), b3 + hstep, voffB); PG8_STAGE(PG8_SA(1, 0), a3, voffA); PG8_STAGEX(1, x3);
.LBB0_1869:
.LBB0_1870:
	s_barrier
	s_mov_b32 m0, s82
	v_lshl_add_u64 v[206:207], v[224:225], 0, s[86:87]
	ds_read_b128 v[198:201], v238 offset:49152
	ds_read_b128 v[202:205], v238 offset:50176
	ds_read_b128 v[190:193], v238 offset:51200
	ds_read_b128 v[194:197], v238 offset:52224
	ds_read_b128 v[182:185], v238 offset:53248
	ds_read_b128 v[186:189], v238 offset:54272
	ds_read_b128 v[174:177], v238 offset:55296
	ds_read_b128 v[178:181], v238 offset:56320
	global_load_lds_dwordx4 v[206:207], off
	v_lshl_add_u64 v[206:207], v[226:227], 0, s[86:87]
	s_mov_b32 m0, s83
	s_nop 0
	global_load_lds_dwordx4 v[206:207], off
	v_lshl_add_u64 v[206:207], v[228:229], 0, s[86:87]
	s_mov_b32 m0, s89
	s_nop 0
	global_load_lds_dwordx4 v[206:207], off
	v_lshl_add_u64 v[206:207], v[230:231], 0, s[86:87]
	s_mov_b32 m0, s92
	s_nop 0
	global_load_lds_dwordx4 v[206:207], off
	v_lshl_add_u64 v[206:207], v[232:233], 0, s[86:87]
	s_mov_b32 m0, s37
	s_nop 0
	global_load_lds_dwordx4 v[206:207], off
	v_lshl_add_u64 v[206:207], v[234:235], 0, s[86:87]
	s_mov_b32 m0, s38
	s_nop 0
	global_load_lds_dwordx4 v[206:207], off
	s_and_saveexec_b64 s[0:1], s[2:3]
	s_cbranch_execz .LBB0_1855
	s_add_i32 s8, s68, 0
	v_lshl_add_u64 v[4:5], v[4:5], 0, s[86:87]
	s_add_i32 m0, s8, 0x22c00
	s_nop 0
	global_load_lds_dwordx4 v[4:5], off
	s_branch .LBB0_1855
